# ret_scan: sh=0 V loads hoisted to the start of the rkT staging section (on top of shared packed-state fragments and integer-RNE output conversion)
# baseline (speedup 1.0000x reference)
.LBB0_327:
	v_mov_b32_e32 v130, s67
	v_mov_b32_e32 v131, s66
	v_cndmask_b32_e32 v130, v130, v131, vcc
	v_lshl_add_u32 v168, v130, 7, v155
	v_mov_b32_e32 v153, v161
	v_mov_b32_e32 v192, v181
	v_mov_b32_e32 v190, v183
	v_mov_b32_e32 v191, v182
	v_mov_b32_e32 v166, v157
	v_mov_b32_e32 v130, v186
	v_mov_b32_e32 v131, v187
	v_ashrrev_i32_e32 v169, 31, v168
	v_readfirstlane_b32 s64, v130
	v_readfirstlane_b32 s65, v131
	v_lshlrev_b64 v[130:131], 11, v[168:169]
	v_mov_b32_e32 v167, v189
	s_barrier
	v_lshl_add_u64 v[130:131], s[64:65], 0, v[130:131]
	v_lshl_add_u64 v[130:131], v[130:131], 0, v[0:1]
	v_lshlrev_b32_e32 v132, 4, v167
	v_and_b32_e32 v198, 0x1f0, v132
	v_mov_b32_e32 v199, v1
	v_lshlrev_b32_e32 v132, 6, v167
	v_lshl_add_u64 v[130:131], v[130:131], 0, v[198:199]
	v_and_b32_e32 v132, 0x3800, v132
	v_mov_b32_e32 v133, v1
	v_lshl_add_u64 v[208:209], v[130:131], 0, v[132:133]
	s_mov_b32 s6, 0xc640000
	v_add_co_u32_e64 v130, s[6:7], s6, v208
	v_bfe_u32 v167, v167, 5, 3
	s_nop 0
	v_addc_co_u32_e64 v131, s[6:7], 0, v209, s[6:7]
	s_mov_b32 s6, 0xc644000
	s_nop 0
	v_add_co_u32_e64 v134, s[6:7], s6, v208
	v_mul_u32_u24_e32 v167, 0x208, v167
	s_nop 0
	v_addc_co_u32_e64 v135, s[6:7], 0, v209, s[6:7]
	s_mov_b32 s6, 0xc648000
	s_nop 0
	v_add_co_u32_e64 v138, s[6:7], s6, v208
	global_load_dwordx4 v[130:133], v[130:131], off
	s_nop 0
	global_load_dwordx4 v[134:137], v[134:135], off
	v_addc_co_u32_e64 v139, s[6:7], 0, v209, s[6:7]
	s_mov_b32 s6, 0xc64c000
	s_nop 0
	v_add_co_u32_e64 v142, s[6:7], s6, v208
	v_add3_u32 v167, v149, v198, v167
	s_nop 0
	v_addc_co_u32_e64 v143, s[6:7], 0, v209, s[6:7]
	s_mov_b32 s6, 0xc650000
	s_nop 0
	v_add_co_u32_e64 v170, s[6:7], s6, v208
	global_load_dwordx4 v[138:141], v[138:139], off
	s_nop 0
	global_load_dwordx4 v[142:145], v[142:143], off
	v_addc_co_u32_e64 v171, s[6:7], 0, v209, s[6:7]
	s_mov_b32 s6, 0xc654000
	s_nop 0
	v_add_co_u32_e64 v194, s[6:7], s6, v208
	v_add_u32_e32 v193, 0x1040, v167
	s_nop 0
	v_addc_co_u32_e64 v195, s[6:7], 0, v209, s[6:7]
	s_mov_b32 s6, 0xc658000
	s_nop 0
	v_add_co_u32_e64 v210, s[6:7], s6, v208
	global_load_dwordx4 v[170:173], v[170:171], off
	s_nop 0
	global_load_dwordx4 v[194:197], v[194:195], off
	v_addc_co_u32_e64 v211, s[6:7], 0, v209, s[6:7]
	s_mov_b32 s6, 0xc65c000
	global_load_dwordx4 v[218:221], v[210:211], off
	v_add_co_u32_e64 v210, s[6:7], s6, v208
	v_add_u32_e32 v198, 0x2080, v167
	s_nop 0
	v_addc_co_u32_e64 v211, s[6:7], 0, v209, s[6:7]
	global_load_dwordx4 v[222:225], v[210:211], off
	v_add_u32_e32 v199, 0x30c0, v167
	v_add_u32_e32 v201, 0x4100, v167
	v_add_u32_e32 v217, 0x5140, v167
	v_lshl_add_u64 v[210:211], s[64:65], 0, v[162:163]
	s_waitcnt vmcnt(7)
	ds_write2_b64 v167, v[130:131], v[132:133] offset1:1
	s_waitcnt vmcnt(6)
	ds_write2_b64 v193, v[134:135], v[136:137] offset1:1
	s_waitcnt vmcnt(5)
	ds_write2_b64 v198, v[138:139], v[140:141] offset1:1
	s_waitcnt vmcnt(4)
	ds_write2_b64 v199, v[142:143], v[144:145] offset1:1
	s_waitcnt vmcnt(3)
	ds_write2_b64 v201, v[170:171], v[172:173] offset1:1
	s_waitcnt vmcnt(2)
	ds_write2_b64 v217, v[194:195], v[196:197] offset1:1
	v_add_u32_e32 v130, 0x6180, v167
	s_waitcnt vmcnt(1)
	ds_write2_b64 v130, v[218:219], v[220:221] offset1:1
	v_add_u32_e32 v130, 0x71c0, v167
	s_waitcnt vmcnt(0)
	ds_write2_b64 v130, v[222:223], v[224:225] offset1:1
	s_mov_b32 s6, 0xc660000
	v_add_co_u32_e64 v130, s[6:7], s6, v208
	v_add_u32_e32 v193, 0x8200, v167
	s_nop 0
	v_addc_co_u32_e64 v131, s[6:7], 0, v209, s[6:7]
	s_mov_b32 s6, 0xc664000
	s_nop 0
	v_add_co_u32_e64 v134, s[6:7], s6, v208
	global_load_dwordx4 v[130:133], v[130:131], off
	s_nop 0
	v_addc_co_u32_e64 v135, s[6:7], 0, v209, s[6:7]
	s_mov_b32 s6, 0xc668000
	s_nop 0
	v_add_co_u32_e64 v138, s[6:7], s6, v208
	global_load_dwordx4 v[134:137], v[134:135], off
	s_nop 0
	v_addc_co_u32_e64 v139, s[6:7], 0, v209, s[6:7]
	s_mov_b32 s6, 0xc66c000
	s_nop 0
	v_add_co_u32_e64 v142, s[6:7], s6, v208
	global_load_dwordx4 v[138:141], v[138:139], off
	s_nop 0
	v_addc_co_u32_e64 v143, s[6:7], 0, v209, s[6:7]
	s_mov_b32 s6, 0xc670000
	s_nop 0
	v_add_co_u32_e64 v170, s[6:7], s6, v208
	global_load_dwordx4 v[142:145], v[142:143], off
	s_nop 0
	v_addc_co_u32_e64 v171, s[6:7], 0, v209, s[6:7]
	s_mov_b32 s6, 0xc674000
	s_nop 0
	v_add_co_u32_e64 v194, s[6:7], s6, v208
	global_load_dwordx4 v[170:173], v[170:171], off
	s_nop 0
	v_addc_co_u32_e64 v195, s[6:7], 0, v209, s[6:7]
	s_mov_b32 s6, 0xc678000
	s_nop 0
	v_add_co_u32_e64 v198, s[6:7], s6, v208
	global_load_dwordx4 v[194:197], v[194:195], off
	s_nop 0
	v_addc_co_u32_e64 v199, s[6:7], 0, v209, s[6:7]
	s_mov_b32 s6, 0xc67c000
	global_load_dwordx4 v[218:221], v[198:199], off
	v_add_co_u32_e64 v198, s[6:7], s6, v208
	s_waitcnt vmcnt(6)
	ds_write2_b64 v193, v[130:131], v[132:133] offset1:1
	v_addc_co_u32_e64 v199, s[6:7], 0, v209, s[6:7]
	global_load_dwordx4 v[222:225], v[198:199], off
	v_add_u32_e32 v130, 0x9240, v167
	s_waitcnt vmcnt(6)
	ds_write2_b64 v130, v[134:135], v[136:137] offset1:1
	v_add_u32_e32 v130, 0xa280, v167
	s_waitcnt vmcnt(5)
	ds_write2_b64 v130, v[138:139], v[140:141] offset1:1
	v_add_u32_e32 v130, 0xb2c0, v167
	s_waitcnt vmcnt(4)
	ds_write2_b64 v130, v[142:143], v[144:145] offset1:1
	v_add_u32_e32 v130, 0xc300, v167
	s_waitcnt vmcnt(3)
	ds_write2_b64 v130, v[170:171], v[172:173] offset1:1
	v_add_u32_e32 v130, 0xd340, v167
	s_waitcnt vmcnt(2)
	ds_write2_b64 v130, v[194:195], v[196:197] offset1:1
	v_add_u32_e32 v130, 0xe380, v167
	s_waitcnt vmcnt(1)
	ds_write2_b64 v130, v[218:219], v[220:221] offset1:1
	v_add_u32_e32 v130, 0xf3c0, v167
	s_waitcnt vmcnt(0)
	ds_write2_b64 v130, v[222:223], v[224:225] offset1:1
	s_waitcnt lgkmcnt(0)
	s_barrier
	v_ashrrev_i32_e32 v167, 31, v166
	v_lshl_add_u64 v[130:131], v[166:167], 1, v[210:211]
	s_mov_b64 s[6:7], 0x8640000
	v_lshl_add_u64 v[170:171], v[130:131], 0, s[6:7]
	v_add_u32_e32 v250, 0x4000, v178
	ds_read2_b64 v[194:197], v178 offset0:0 offset1:2
	ds_read2_b64 v[218:221], v250 offset0:32 offset1:34
	ds_read2_b64 v[222:225], v178 offset0:4 offset1:6
	ds_read2_b64 v[226:229], v250 offset0:36 offset1:38
	s_nop 0
	v_cvt_pk_bf16_f32 v230, v2, v3
	v_cvt_pk_bf16_f32 v231, v4, v5
	v_cvt_pk_bf16_f32 v232, v6, v7
	v_cvt_pk_bf16_f32 v233, v8, v9
	s_waitcnt lgkmcnt(2)
	s_nop 1
	v_mfma_f32_32x32x16_bf16 v[130:145], v[194:197], v[230:233], 0
	v_mfma_f32_32x32x16_bf16 v[234:249], v[218:221], v[230:233], 0
	ds_read2_b64 v[194:197], v178 offset0:8 offset1:10
	ds_read2_b64 v[218:221], v250 offset0:40 offset1:42
	s_nop 0
	v_cvt_pk_bf16_f32 v230, v10, v11
	v_cvt_pk_bf16_f32 v231, v12, v13
	v_cvt_pk_bf16_f32 v232, v14, v15
	v_cvt_pk_bf16_f32 v233, v16, v17
	s_waitcnt lgkmcnt(2)
	s_nop 1
	v_mfma_f32_32x32x16_bf16 v[130:145], v[222:225], v[230:233], v[130:145]
	v_mfma_f32_32x32x16_bf16 v[234:249], v[226:229], v[230:233], v[234:249]
	ds_read2_b64 v[222:225], v178 offset0:12 offset1:14
	ds_read2_b64 v[226:229], v250 offset0:44 offset1:46
	s_nop 0
	v_cvt_pk_bf16_f32 v230, v18, v19
	v_cvt_pk_bf16_f32 v231, v20, v21
	v_cvt_pk_bf16_f32 v232, v22, v23
	v_cvt_pk_bf16_f32 v233, v24, v25
	s_waitcnt lgkmcnt(2)
	s_nop 1
	v_mfma_f32_32x32x16_bf16 v[130:145], v[194:197], v[230:233], v[130:145]
	v_mfma_f32_32x32x16_bf16 v[234:249], v[218:221], v[230:233], v[234:249]
	ds_read2_b64 v[194:197], v178 offset0:16 offset1:18
	ds_read2_b64 v[218:221], v250 offset0:48 offset1:50
	s_nop 0
	v_cvt_pk_bf16_f32 v230, v26, v27
	v_cvt_pk_bf16_f32 v231, v28, v29
	v_cvt_pk_bf16_f32 v232, v30, v31
	v_cvt_pk_bf16_f32 v233, v32, v33
	s_waitcnt lgkmcnt(2)
	s_nop 1
	v_mfma_f32_32x32x16_bf16 v[130:145], v[222:225], v[230:233], v[130:145]
	v_mfma_f32_32x32x16_bf16 v[234:249], v[226:229], v[230:233], v[234:249]
	ds_read2_b64 v[222:225], v178 offset0:20 offset1:22
	ds_read2_b64 v[226:229], v250 offset0:52 offset1:54
	s_nop 0
	v_cvt_pk_bf16_f32 v230, v34, v35
	v_cvt_pk_bf16_f32 v231, v36, v37
	v_cvt_pk_bf16_f32 v232, v38, v39
	v_cvt_pk_bf16_f32 v233, v40, v41
	s_waitcnt lgkmcnt(2)
	s_nop 1
	v_mfma_f32_32x32x16_bf16 v[130:145], v[194:197], v[230:233], v[130:145]
	v_mfma_f32_32x32x16_bf16 v[234:249], v[218:221], v[230:233], v[234:249]
	ds_read2_b64 v[194:197], v178 offset0:24 offset1:26
	ds_read2_b64 v[218:221], v250 offset0:56 offset1:58
	s_nop 0
	v_cvt_pk_bf16_f32 v230, v42, v43
	v_cvt_pk_bf16_f32 v231, v44, v45
	v_cvt_pk_bf16_f32 v232, v46, v47
	v_cvt_pk_bf16_f32 v233, v48, v49
	s_waitcnt lgkmcnt(2)
	s_nop 1
	v_mfma_f32_32x32x16_bf16 v[130:145], v[222:225], v[230:233], v[130:145]
	v_mfma_f32_32x32x16_bf16 v[234:249], v[226:229], v[230:233], v[234:249]
	ds_read2_b64 v[222:225], v178 offset0:28 offset1:30
	ds_read2_b64 v[226:229], v250 offset0:60 offset1:62
	s_nop 0
	v_cvt_pk_bf16_f32 v230, v50, v51
	v_cvt_pk_bf16_f32 v231, v52, v53
	v_cvt_pk_bf16_f32 v232, v54, v55
	v_cvt_pk_bf16_f32 v233, v56, v57
	s_waitcnt lgkmcnt(2)
	s_nop 1
	v_mfma_f32_32x32x16_bf16 v[130:145], v[194:197], v[230:233], v[130:145]
	v_mfma_f32_32x32x16_bf16 v[234:249], v[218:221], v[230:233], v[234:249]
	ds_read2_b64 v[194:197], v178 offset0:32 offset1:34
	ds_read2_b64 v[218:221], v250 offset0:64 offset1:66
	s_nop 0
	v_cvt_pk_bf16_f32 v230, v58, v59
	v_cvt_pk_bf16_f32 v231, v60, v61
	v_cvt_pk_bf16_f32 v232, v62, v63
	v_cvt_pk_bf16_f32 v233, v64, v65
	s_waitcnt lgkmcnt(2)
	s_nop 1
	v_mfma_f32_32x32x16_bf16 v[130:145], v[222:225], v[230:233], v[130:145]
	v_mfma_f32_32x32x16_bf16 v[234:249], v[226:229], v[230:233], v[234:249]
	ds_read2_b64 v[222:225], v178 offset0:36 offset1:38
	ds_read2_b64 v[226:229], v250 offset0:68 offset1:70
	s_nop 0
	v_cvt_pk_bf16_f32 v230, v66, v67
	v_cvt_pk_bf16_f32 v231, v68, v69
	v_cvt_pk_bf16_f32 v232, v70, v71
	v_cvt_pk_bf16_f32 v233, v72, v73
	s_waitcnt lgkmcnt(2)
	s_nop 1
	v_mfma_f32_32x32x16_bf16 v[130:145], v[194:197], v[230:233], v[130:145]
	v_mfma_f32_32x32x16_bf16 v[234:249], v[218:221], v[230:233], v[234:249]
	ds_read2_b64 v[194:197], v178 offset0:40 offset1:42
	ds_read2_b64 v[218:221], v250 offset0:72 offset1:74
	s_nop 0
	v_cvt_pk_bf16_f32 v230, v74, v75
	v_cvt_pk_bf16_f32 v231, v76, v77
	v_cvt_pk_bf16_f32 v232, v78, v79
	v_cvt_pk_bf16_f32 v233, v80, v81
	s_waitcnt lgkmcnt(2)
	s_nop 1
	v_mfma_f32_32x32x16_bf16 v[130:145], v[222:225], v[230:233], v[130:145]
	v_mfma_f32_32x32x16_bf16 v[234:249], v[226:229], v[230:233], v[234:249]
	ds_read2_b64 v[222:225], v178 offset0:44 offset1:46
	ds_read2_b64 v[226:229], v250 offset0:76 offset1:78
	s_nop 0
	v_cvt_pk_bf16_f32 v230, v82, v83
	v_cvt_pk_bf16_f32 v231, v84, v85
	v_cvt_pk_bf16_f32 v232, v86, v87
	v_cvt_pk_bf16_f32 v233, v88, v89
	s_waitcnt lgkmcnt(2)
	s_nop 1
	v_mfma_f32_32x32x16_bf16 v[130:145], v[194:197], v[230:233], v[130:145]
	v_mfma_f32_32x32x16_bf16 v[234:249], v[218:221], v[230:233], v[234:249]
	ds_read2_b64 v[194:197], v178 offset0:48 offset1:50
	ds_read2_b64 v[218:221], v250 offset0:80 offset1:82
	s_nop 0
	v_cvt_pk_bf16_f32 v230, v90, v91
	v_cvt_pk_bf16_f32 v231, v92, v93
	v_cvt_pk_bf16_f32 v232, v94, v95
	v_cvt_pk_bf16_f32 v233, v96, v97
	s_waitcnt lgkmcnt(2)
	s_nop 1
	v_mfma_f32_32x32x16_bf16 v[130:145], v[222:225], v[230:233], v[130:145]
	v_mfma_f32_32x32x16_bf16 v[234:249], v[226:229], v[230:233], v[234:249]
	ds_read2_b64 v[222:225], v178 offset0:52 offset1:54
	ds_read2_b64 v[226:229], v250 offset0:84 offset1:86
	s_nop 0
	v_cvt_pk_bf16_f32 v230, v98, v99
	v_cvt_pk_bf16_f32 v231, v100, v101
	v_cvt_pk_bf16_f32 v232, v102, v103
	v_cvt_pk_bf16_f32 v233, v104, v105
	s_waitcnt lgkmcnt(2)
	s_nop 1
	v_mfma_f32_32x32x16_bf16 v[130:145], v[194:197], v[230:233], v[130:145]
	v_mfma_f32_32x32x16_bf16 v[234:249], v[218:221], v[230:233], v[234:249]
	ds_read2_b64 v[194:197], v178 offset0:56 offset1:58
	ds_read2_b64 v[218:221], v250 offset0:88 offset1:90
	s_nop 0
	v_cvt_pk_bf16_f32 v230, v106, v107
	v_cvt_pk_bf16_f32 v231, v108, v109
	v_cvt_pk_bf16_f32 v232, v110, v111
	v_cvt_pk_bf16_f32 v233, v112, v113
	s_waitcnt lgkmcnt(2)
	s_nop 1
	v_mfma_f32_32x32x16_bf16 v[130:145], v[222:225], v[230:233], v[130:145]
	v_mfma_f32_32x32x16_bf16 v[234:249], v[226:229], v[230:233], v[234:249]
	ds_read2_b64 v[222:225], v178 offset0:60 offset1:62
	ds_read2_b64 v[226:229], v250 offset0:92 offset1:94
	s_nop 0
	v_cvt_pk_bf16_f32 v230, v114, v115
	v_cvt_pk_bf16_f32 v231, v116, v117
	v_cvt_pk_bf16_f32 v232, v118, v119
	v_cvt_pk_bf16_f32 v233, v120, v121
	s_waitcnt lgkmcnt(2)
	s_nop 1
	v_mfma_f32_32x32x16_bf16 v[130:145], v[194:197], v[230:233], v[130:145]
	v_mfma_f32_32x32x16_bf16 v[234:249], v[218:221], v[230:233], v[234:249]
	s_nop 0
	v_cvt_pk_bf16_f32 v230, v122, v123
	v_cvt_pk_bf16_f32 v231, v124, v125
	v_cvt_pk_bf16_f32 v232, v126, v127
	v_cvt_pk_bf16_f32 v233, v128, v129
	s_waitcnt lgkmcnt(0)
	s_nop 1
	v_mfma_f32_32x32x16_bf16 v[130:145], v[222:225], v[230:233], v[130:145]
	v_mfma_f32_32x32x16_bf16 v[234:249], v[226:229], v[230:233], v[234:249]
	v_or_b32_e32 v172, v168, v174
	v_ashrrev_i32_e32 v173, 31, v172
	v_fma_f32 v193, 0, v192, v153
	v_exp_f32_e32 v193, v193
	v_lshlrev_b64 v[172:173], 12, v[172:173]
	v_lshl_add_u64 v[194:195], v[170:171], 0, v[172:173]
	s_nop 7
	v_mul_f32_e32 v130, v193, v130
	v_mov_b32_e32 v251, 0x7fff
	v_bfe_u32 v250, v130, 16, 1
	v_add3_u32 v130, v130, v250, v251
	global_store_short_d16_hi v[194:195], v130, off
	v_add_f32_e32 v130, v153, v192
	v_exp_f32_e32 v130, v130
	s_nop 0
	v_mul_f32_e32 v130, v130, v131
	v_bfe_u32 v250, v130, 16, 1
	v_add3_u32 v193, v130, v250, v251
	v_or_b32_e32 v130, 0x1000, v172
	v_mov_b32_e32 v131, v173
	v_lshl_add_u64 v[130:131], v[170:171], 0, v[130:131]
	global_store_short_d16_hi v[130:131], v193, off
	v_fma_f32 v130, 2.0, v192, v153
	v_exp_f32_e32 v130, v130
	v_mov_b32_e32 v131, v173
	v_mul_f32_e32 v130, v130, v132
	v_bfe_u32 v250, v130, 16, 1
	v_add3_u32 v132, v130, v250, v251
	v_or_b32_e32 v130, 0x2000, v172
	v_lshl_add_u64 v[130:131], v[170:171], 0, v[130:131]
	global_store_short_d16_hi v[130:131], v132, off
	v_fmamk_f32 v130, v192, 0x40400000, v153
	v_exp_f32_e32 v130, v130
	v_mov_b32_e32 v131, v173
	v_mul_f32_e32 v130, v130, v133
	v_bfe_u32 v250, v130, 16, 1
	v_add3_u32 v132, v130, v250, v251
	v_or_b32_e32 v130, 0x3000, v172
	v_lshl_add_u64 v[130:131], v[170:171], 0, v[130:131]
	global_store_short_d16_hi v[130:131], v132, off
	v_fmamk_f32 v130, v192, 0x41000000, v153
	v_exp_f32_e32 v130, v130
	v_mov_b32_e32 v131, v173
	v_mul_f32_e32 v130, v130, v134
	v_bfe_u32 v250, v130, 16, 1
	v_add3_u32 v132, v130, v250, v251
	v_or_b32_e32 v130, 0x8000, v172
	v_lshl_add_u64 v[130:131], v[170:171], 0, v[130:131]
	global_store_short_d16_hi v[130:131], v132, off
	v_fmamk_f32 v130, v192, 0x41100000, v153
	v_exp_f32_e32 v130, v130
	v_mov_b32_e32 v131, v173
	v_mul_f32_e32 v130, v130, v135
	v_bfe_u32 v250, v130, 16, 1
	v_add3_u32 v132, v130, v250, v251
	v_or_b32_e32 v130, 0x9000, v172
	v_lshl_add_u64 v[130:131], v[170:171], 0, v[130:131]
	global_store_short_d16_hi v[130:131], v132, off
	v_fmamk_f32 v130, v192, 0x41200000, v153
	v_exp_f32_e32 v130, v130
	v_mov_b32_e32 v131, v173
	v_mul_f32_e32 v130, v130, v136
	v_bfe_u32 v250, v130, 16, 1
	v_add3_u32 v132, v130, v250, v251
	v_or_b32_e32 v130, 0xa000, v172
	v_lshl_add_u64 v[130:131], v[170:171], 0, v[130:131]
	global_store_short_d16_hi v[130:131], v132, off
	v_fmamk_f32 v130, v192, 0x41300000, v153
	v_exp_f32_e32 v130, v130
	v_mov_b32_e32 v131, v173
	v_mul_f32_e32 v130, v130, v137
	v_bfe_u32 v250, v130, 16, 1
	v_add3_u32 v132, v130, v250, v251
	v_or_b32_e32 v130, 0xb000, v172
	v_lshl_add_u64 v[130:131], v[170:171], 0, v[130:131]
	global_store_short_d16_hi v[130:131], v132, off
	v_fmamk_f32 v130, v192, 0x41800000, v153
	v_exp_f32_e32 v130, v130
	v_mov_b32_e32 v131, v173
	v_mul_f32_e32 v130, v130, v138
	v_bfe_u32 v250, v130, 16, 1
	v_add3_u32 v132, v130, v250, v251
	v_or_b32_e32 v130, 0x10000, v172
	v_lshl_add_u64 v[130:131], v[170:171], 0, v[130:131]
	global_store_short_d16_hi v[130:131], v132, off
	v_fmamk_f32 v130, v192, 0x41880000, v153
	v_exp_f32_e32 v130, v130
	v_mov_b32_e32 v131, v173
	v_mul_f32_e32 v130, v130, v139
	v_bfe_u32 v250, v130, 16, 1
	v_add3_u32 v132, v130, v250, v251
	v_or_b32_e32 v130, 0x11000, v172
	v_lshl_add_u64 v[130:131], v[170:171], 0, v[130:131]
	global_store_short_d16_hi v[130:131], v132, off
	v_fmamk_f32 v130, v192, 0x41900000, v153
	v_exp_f32_e32 v130, v130
	v_mov_b32_e32 v131, v173
	v_mul_f32_e32 v130, v130, v140
	v_bfe_u32 v250, v130, 16, 1
	v_add3_u32 v132, v130, v250, v251
	v_or_b32_e32 v130, 0x12000, v172
	v_lshl_add_u64 v[130:131], v[170:171], 0, v[130:131]
	global_store_short_d16_hi v[130:131], v132, off
	v_fmamk_f32 v130, v192, 0x41980000, v153
	v_exp_f32_e32 v130, v130
	v_mov_b32_e32 v131, v173
	v_mul_f32_e32 v130, v130, v141
	v_bfe_u32 v250, v130, 16, 1
	v_add3_u32 v132, v130, v250, v251
	v_or_b32_e32 v130, 0x13000, v172
	v_lshl_add_u64 v[130:131], v[170:171], 0, v[130:131]
	global_store_short_d16_hi v[130:131], v132, off
	v_fmamk_f32 v130, v192, 0x41c00000, v153
	v_exp_f32_e32 v130, v130
	v_mov_b32_e32 v131, v173
	v_mul_f32_e32 v130, v130, v142
	v_bfe_u32 v250, v130, 16, 1
	v_add3_u32 v132, v130, v250, v251
	v_or_b32_e32 v130, 0x18000, v172
	v_lshl_add_u64 v[130:131], v[170:171], 0, v[130:131]
	global_store_short_d16_hi v[130:131], v132, off
	v_fmamk_f32 v130, v192, 0x41c80000, v153
	v_exp_f32_e32 v130, v130
	v_mov_b32_e32 v131, v173
	v_mul_f32_e32 v130, v130, v143
	v_bfe_u32 v250, v130, 16, 1
	v_add3_u32 v132, v130, v250, v251
	v_or_b32_e32 v130, 0x19000, v172
	v_lshl_add_u64 v[130:131], v[170:171], 0, v[130:131]
	global_store_short_d16_hi v[130:131], v132, off
	v_fmamk_f32 v130, v192, 0x41d00000, v153
	v_exp_f32_e32 v130, v130
	v_mov_b32_e32 v131, v173
	v_mul_f32_e32 v130, v130, v144
	v_bfe_u32 v250, v130, 16, 1
	v_add3_u32 v132, v130, v250, v251
	v_or_b32_e32 v130, 0x1a000, v172
	v_lshl_add_u64 v[130:131], v[170:171], 0, v[130:131]
	global_store_short_d16_hi v[130:131], v132, off
	v_fmamk_f32 v130, v192, 0x41d80000, v153
	v_exp_f32_e32 v130, v130
	v_mov_b32_e32 v131, v173
	v_mul_f32_e32 v130, v130, v145
	v_bfe_u32 v250, v130, 16, 1
	v_add3_u32 v132, v130, v250, v251
	v_or_b32_e32 v130, 0x1b000, v172
	v_lshl_add_u64 v[130:131], v[170:171], 0, v[130:131]
	global_store_short_d16_hi v[130:131], v132, off
	v_mov_b32_e32 v130, v234
	v_mov_b32_e32 v131, v235
	v_mov_b32_e32 v132, v236
	v_mov_b32_e32 v133, v237
	v_mov_b32_e32 v134, v238
	v_mov_b32_e32 v135, v239
	v_mov_b32_e32 v136, v240
	v_mov_b32_e32 v137, v241
	v_mov_b32_e32 v138, v242
	v_mov_b32_e32 v139, v243
	v_mov_b32_e32 v140, v244
	v_mov_b32_e32 v141, v245
	v_mov_b32_e32 v142, v246
	v_mov_b32_e32 v143, v247
	v_mov_b32_e32 v144, v248
	v_mov_b32_e32 v145, v249
	v_fmamk_f32 v193, v192, 0x42000000, v153
	v_exp_f32_e32 v193, v193
	v_or_b32_e32 v194, 0x20000, v172
	v_mov_b32_e32 v195, v173
	v_lshl_add_u64 v[194:195], v[170:171], 0, v[194:195]
	s_nop 6
	v_mul_f32_e32 v130, v193, v130
	v_mov_b32_e32 v251, 0x7fff
	v_bfe_u32 v250, v130, 16, 1
	v_add3_u32 v130, v130, v250, v251
	global_store_short_d16_hi v[194:195], v130, off
	v_fmamk_f32 v130, v192, 0x42040000, v153
	v_exp_f32_e32 v130, v130
	s_nop 0
	v_mul_f32_e32 v130, v130, v131
	v_bfe_u32 v250, v130, 16, 1
	v_add3_u32 v193, v130, v250, v251
	v_or_b32_e32 v130, 0x21000, v172
	v_mov_b32_e32 v131, v173
	v_lshl_add_u64 v[130:131], v[170:171], 0, v[130:131]
	global_store_short_d16_hi v[130:131], v193, off
	v_fmamk_f32 v130, v192, 0x42080000, v153
	v_exp_f32_e32 v130, v130
	v_mov_b32_e32 v131, v173
	v_mul_f32_e32 v130, v130, v132
	v_bfe_u32 v250, v130, 16, 1
	v_add3_u32 v132, v130, v250, v251
	v_or_b32_e32 v130, 0x22000, v172
	v_lshl_add_u64 v[130:131], v[170:171], 0, v[130:131]
	global_store_short_d16_hi v[130:131], v132, off
	v_fmamk_f32 v130, v192, 0x420c0000, v153
	v_exp_f32_e32 v130, v130
	v_mov_b32_e32 v131, v173
	v_mul_f32_e32 v130, v130, v133
	v_bfe_u32 v250, v130, 16, 1
	v_add3_u32 v132, v130, v250, v251
	v_or_b32_e32 v130, 0x23000, v172
	v_lshl_add_u64 v[130:131], v[170:171], 0, v[130:131]
	global_store_short_d16_hi v[130:131], v132, off
	v_fmamk_f32 v130, v192, 0x42200000, v153
	v_exp_f32_e32 v130, v130
	v_mov_b32_e32 v131, v173
	v_mul_f32_e32 v130, v130, v134
	v_bfe_u32 v250, v130, 16, 1
	v_add3_u32 v132, v130, v250, v251
	v_or_b32_e32 v130, 0x28000, v172
	v_lshl_add_u64 v[130:131], v[170:171], 0, v[130:131]
	global_store_short_d16_hi v[130:131], v132, off
	v_fmamk_f32 v130, v192, 0x42240000, v153
	v_exp_f32_e32 v130, v130
	v_mov_b32_e32 v131, v173
	v_mul_f32_e32 v130, v130, v135
	v_bfe_u32 v250, v130, 16, 1
	v_add3_u32 v132, v130, v250, v251
	v_or_b32_e32 v130, 0x29000, v172
	v_lshl_add_u64 v[130:131], v[170:171], 0, v[130:131]
	global_store_short_d16_hi v[130:131], v132, off
	v_fmamk_f32 v130, v192, 0x42280000, v153
	v_exp_f32_e32 v130, v130
	v_mov_b32_e32 v131, v173
	v_mul_f32_e32 v130, v130, v136
	v_bfe_u32 v250, v130, 16, 1
	v_add3_u32 v132, v130, v250, v251
	v_or_b32_e32 v130, 0x2a000, v172
	v_lshl_add_u64 v[130:131], v[170:171], 0, v[130:131]
	global_store_short_d16_hi v[130:131], v132, off
	v_fmamk_f32 v130, v192, 0x422c0000, v153
	v_exp_f32_e32 v130, v130
	v_mov_b32_e32 v131, v173
	v_mul_f32_e32 v130, v130, v137
	v_bfe_u32 v250, v130, 16, 1
	v_add3_u32 v132, v130, v250, v251
	v_or_b32_e32 v130, 0x2b000, v172
	v_lshl_add_u64 v[130:131], v[170:171], 0, v[130:131]
	global_store_short_d16_hi v[130:131], v132, off
	v_fmamk_f32 v130, v192, 0x42400000, v153
	v_exp_f32_e32 v130, v130
	v_mov_b32_e32 v131, v173
	v_mul_f32_e32 v130, v130, v138
	v_bfe_u32 v250, v130, 16, 1
	v_add3_u32 v132, v130, v250, v251
	v_or_b32_e32 v130, 0x30000, v172
	v_lshl_add_u64 v[130:131], v[170:171], 0, v[130:131]
	global_store_short_d16_hi v[130:131], v132, off
	v_fmamk_f32 v130, v192, 0x42440000, v153
	v_exp_f32_e32 v130, v130
	v_mov_b32_e32 v131, v173
	v_mul_f32_e32 v130, v130, v139
	v_bfe_u32 v250, v130, 16, 1
	v_add3_u32 v132, v130, v250, v251
	v_or_b32_e32 v130, 0x31000, v172
	v_lshl_add_u64 v[130:131], v[170:171], 0, v[130:131]
	global_store_short_d16_hi v[130:131], v132, off
	v_fmamk_f32 v130, v192, 0x42480000, v153
	v_exp_f32_e32 v130, v130
	v_mov_b32_e32 v131, v173
	v_mul_f32_e32 v130, v130, v140
	v_bfe_u32 v250, v130, 16, 1
	v_add3_u32 v132, v130, v250, v251
	v_or_b32_e32 v130, 0x32000, v172
	v_lshl_add_u64 v[130:131], v[170:171], 0, v[130:131]
	global_store_short_d16_hi v[130:131], v132, off
	v_fmamk_f32 v130, v192, 0x424c0000, v153
	v_exp_f32_e32 v130, v130
	v_mov_b32_e32 v131, v173
	v_mul_f32_e32 v130, v130, v141
	v_bfe_u32 v250, v130, 16, 1
	v_add3_u32 v132, v130, v250, v251
	v_or_b32_e32 v130, 0x33000, v172
	v_lshl_add_u64 v[130:131], v[170:171], 0, v[130:131]
	global_store_short_d16_hi v[130:131], v132, off
	v_fmamk_f32 v130, v192, 0x42600000, v153
	v_exp_f32_e32 v130, v130
	v_mov_b32_e32 v131, v173
	v_mul_f32_e32 v130, v130, v142
	v_bfe_u32 v250, v130, 16, 1
	v_add3_u32 v132, v130, v250, v251
	v_or_b32_e32 v130, 0x38000, v172
	v_lshl_add_u64 v[130:131], v[170:171], 0, v[130:131]
	global_store_short_d16_hi v[130:131], v132, off
	v_fmamk_f32 v130, v192, 0x42640000, v153
	v_exp_f32_e32 v130, v130
	v_mov_b32_e32 v131, v173
	v_mul_f32_e32 v130, v130, v143
	v_bfe_u32 v250, v130, 16, 1
	v_add3_u32 v132, v130, v250, v251
	v_or_b32_e32 v130, 0x39000, v172
	v_lshl_add_u64 v[130:131], v[170:171], 0, v[130:131]
	global_store_short_d16_hi v[130:131], v132, off
	v_fmamk_f32 v130, v192, 0x42680000, v153
	v_exp_f32_e32 v130, v130
	v_mov_b32_e32 v131, v173
	v_mul_f32_e32 v130, v130, v144
	v_bfe_u32 v250, v130, 16, 1
	v_add3_u32 v132, v130, v250, v251
	v_or_b32_e32 v130, 0x3a000, v172
	v_lshl_add_u64 v[130:131], v[170:171], 0, v[130:131]
	global_store_short_d16_hi v[130:131], v132, off
	v_fmamk_f32 v130, v192, 0x426c0000, v153
	v_exp_f32_e32 v130, v130
	v_mov_b32_e32 v131, v173
	v_mul_f32_e32 v130, v130, v145
	v_bfe_u32 v250, v130, 16, 1
	v_add3_u32 v132, v130, v250, v251
	v_or_b32_e32 v130, 0x3b000, v172
	v_lshl_add_u64 v[130:131], v[170:171], 0, v[130:131]
	global_store_short_d16_hi v[130:131], v132, off
	v_add_u32_e32 v250, 0xc000, v178
	v_add_u32_e32 v251, 0x8000, v178
	ds_read2_b64 v[194:197], v251 offset0:64 offset1:66
	ds_read2_b64 v[218:221], v250 offset0:96 offset1:98
	ds_read2_b64 v[222:225], v251 offset0:68 offset1:70
	ds_read2_b64 v[226:229], v250 offset0:100 offset1:102
	s_nop 0
	v_cvt_pk_bf16_f32 v230, v2, v3
	v_cvt_pk_bf16_f32 v231, v4, v5
	v_cvt_pk_bf16_f32 v232, v6, v7
	v_cvt_pk_bf16_f32 v233, v8, v9
	s_waitcnt lgkmcnt(2)
	s_nop 1
	v_mfma_f32_32x32x16_bf16 v[130:145], v[194:197], v[230:233], 0
	v_mfma_f32_32x32x16_bf16 v[234:249], v[218:221], v[230:233], 0
	ds_read2_b64 v[194:197], v251 offset0:72 offset1:74
	ds_read2_b64 v[218:221], v250 offset0:104 offset1:106
	s_nop 0
	v_cvt_pk_bf16_f32 v230, v10, v11
	v_cvt_pk_bf16_f32 v231, v12, v13
	v_cvt_pk_bf16_f32 v232, v14, v15
	v_cvt_pk_bf16_f32 v233, v16, v17
	s_waitcnt lgkmcnt(2)
	s_nop 1
	v_mfma_f32_32x32x16_bf16 v[130:145], v[222:225], v[230:233], v[130:145]
	v_mfma_f32_32x32x16_bf16 v[234:249], v[226:229], v[230:233], v[234:249]
	ds_read2_b64 v[222:225], v251 offset0:76 offset1:78
	ds_read2_b64 v[226:229], v250 offset0:108 offset1:110
	s_nop 0
	v_cvt_pk_bf16_f32 v230, v18, v19
	v_cvt_pk_bf16_f32 v231, v20, v21
	v_cvt_pk_bf16_f32 v232, v22, v23
	v_cvt_pk_bf16_f32 v233, v24, v25
	s_waitcnt lgkmcnt(2)
	s_nop 1
	v_mfma_f32_32x32x16_bf16 v[130:145], v[194:197], v[230:233], v[130:145]
	v_mfma_f32_32x32x16_bf16 v[234:249], v[218:221], v[230:233], v[234:249]
	ds_read2_b64 v[194:197], v251 offset0:80 offset1:82
	ds_read2_b64 v[218:221], v250 offset0:112 offset1:114
	s_nop 0
	v_cvt_pk_bf16_f32 v230, v26, v27
	v_cvt_pk_bf16_f32 v231, v28, v29
	v_cvt_pk_bf16_f32 v232, v30, v31
	v_cvt_pk_bf16_f32 v233, v32, v33
	s_waitcnt lgkmcnt(2)
	s_nop 1
	v_mfma_f32_32x32x16_bf16 v[130:145], v[222:225], v[230:233], v[130:145]
	v_mfma_f32_32x32x16_bf16 v[234:249], v[226:229], v[230:233], v[234:249]
	ds_read2_b64 v[222:225], v251 offset0:84 offset1:86
	ds_read2_b64 v[226:229], v250 offset0:116 offset1:118
	s_nop 0
	v_cvt_pk_bf16_f32 v230, v34, v35
	v_cvt_pk_bf16_f32 v231, v36, v37
	v_cvt_pk_bf16_f32 v232, v38, v39
	v_cvt_pk_bf16_f32 v233, v40, v41
	s_waitcnt lgkmcnt(2)
	s_nop 1
	v_mfma_f32_32x32x16_bf16 v[130:145], v[194:197], v[230:233], v[130:145]
	v_mfma_f32_32x32x16_bf16 v[234:249], v[218:221], v[230:233], v[234:249]
	ds_read2_b64 v[194:197], v251 offset0:88 offset1:90
	ds_read2_b64 v[218:221], v250 offset0:120 offset1:122
	s_nop 0
	v_cvt_pk_bf16_f32 v230, v42, v43
	v_cvt_pk_bf16_f32 v231, v44, v45
	v_cvt_pk_bf16_f32 v232, v46, v47
	v_cvt_pk_bf16_f32 v233, v48, v49
	s_waitcnt lgkmcnt(2)
	s_nop 1
	v_mfma_f32_32x32x16_bf16 v[130:145], v[222:225], v[230:233], v[130:145]
	v_mfma_f32_32x32x16_bf16 v[234:249], v[226:229], v[230:233], v[234:249]
	ds_read2_b64 v[222:225], v251 offset0:92 offset1:94
	ds_read2_b64 v[226:229], v250 offset0:124 offset1:126
	s_nop 0
	v_cvt_pk_bf16_f32 v230, v50, v51
	v_cvt_pk_bf16_f32 v231, v52, v53
	v_cvt_pk_bf16_f32 v232, v54, v55
	v_cvt_pk_bf16_f32 v233, v56, v57
	s_waitcnt lgkmcnt(2)
	s_nop 1
	v_mfma_f32_32x32x16_bf16 v[130:145], v[194:197], v[230:233], v[130:145]
	v_mfma_f32_32x32x16_bf16 v[234:249], v[218:221], v[230:233], v[234:249]
	ds_read2_b64 v[194:197], v251 offset0:96 offset1:98
	ds_read2_b64 v[218:221], v250 offset0:128 offset1:130
	s_nop 0
	v_cvt_pk_bf16_f32 v230, v58, v59
	v_cvt_pk_bf16_f32 v231, v60, v61
	v_cvt_pk_bf16_f32 v232, v62, v63
	v_cvt_pk_bf16_f32 v233, v64, v65
	s_waitcnt lgkmcnt(2)
	s_nop 1
	v_mfma_f32_32x32x16_bf16 v[130:145], v[222:225], v[230:233], v[130:145]
	v_mfma_f32_32x32x16_bf16 v[234:249], v[226:229], v[230:233], v[234:249]
	ds_read2_b64 v[222:225], v251 offset0:100 offset1:102
	ds_read2_b64 v[226:229], v250 offset0:132 offset1:134
	s_nop 0
	v_cvt_pk_bf16_f32 v230, v66, v67
	v_cvt_pk_bf16_f32 v231, v68, v69
	v_cvt_pk_bf16_f32 v232, v70, v71
	v_cvt_pk_bf16_f32 v233, v72, v73
	s_waitcnt lgkmcnt(2)
	s_nop 1
	v_mfma_f32_32x32x16_bf16 v[130:145], v[194:197], v[230:233], v[130:145]
	v_mfma_f32_32x32x16_bf16 v[234:249], v[218:221], v[230:233], v[234:249]
	ds_read2_b64 v[194:197], v251 offset0:104 offset1:106
	ds_read2_b64 v[218:221], v250 offset0:136 offset1:138
	s_nop 0
	v_cvt_pk_bf16_f32 v230, v74, v75
	v_cvt_pk_bf16_f32 v231, v76, v77
	v_cvt_pk_bf16_f32 v232, v78, v79
	v_cvt_pk_bf16_f32 v233, v80, v81
	s_waitcnt lgkmcnt(2)
	s_nop 1
	v_mfma_f32_32x32x16_bf16 v[130:145], v[222:225], v[230:233], v[130:145]
	v_mfma_f32_32x32x16_bf16 v[234:249], v[226:229], v[230:233], v[234:249]
	ds_read2_b64 v[222:225], v251 offset0:108 offset1:110
	ds_read2_b64 v[226:229], v250 offset0:140 offset1:142
	s_nop 0
	v_cvt_pk_bf16_f32 v230, v82, v83
	v_cvt_pk_bf16_f32 v231, v84, v85
	v_cvt_pk_bf16_f32 v232, v86, v87
	v_cvt_pk_bf16_f32 v233, v88, v89
	s_waitcnt lgkmcnt(2)
	s_nop 1
	v_mfma_f32_32x32x16_bf16 v[130:145], v[194:197], v[230:233], v[130:145]
	v_mfma_f32_32x32x16_bf16 v[234:249], v[218:221], v[230:233], v[234:249]
	ds_read2_b64 v[194:197], v251 offset0:112 offset1:114
	ds_read2_b64 v[218:221], v250 offset0:144 offset1:146
	s_nop 0
	v_cvt_pk_bf16_f32 v230, v90, v91
	v_cvt_pk_bf16_f32 v231, v92, v93
	v_cvt_pk_bf16_f32 v232, v94, v95
	v_cvt_pk_bf16_f32 v233, v96, v97
	s_waitcnt lgkmcnt(2)
	s_nop 1
	v_mfma_f32_32x32x16_bf16 v[130:145], v[222:225], v[230:233], v[130:145]
	v_mfma_f32_32x32x16_bf16 v[234:249], v[226:229], v[230:233], v[234:249]
	ds_read2_b64 v[222:225], v251 offset0:116 offset1:118
	ds_read2_b64 v[226:229], v250 offset0:148 offset1:150
	s_nop 0
	v_cvt_pk_bf16_f32 v230, v98, v99
	v_cvt_pk_bf16_f32 v231, v100, v101
	v_cvt_pk_bf16_f32 v232, v102, v103
	v_cvt_pk_bf16_f32 v233, v104, v105
	s_waitcnt lgkmcnt(2)
	s_nop 1
	v_mfma_f32_32x32x16_bf16 v[130:145], v[194:197], v[230:233], v[130:145]
	v_mfma_f32_32x32x16_bf16 v[234:249], v[218:221], v[230:233], v[234:249]
	ds_read2_b64 v[194:197], v251 offset0:120 offset1:122
	ds_read2_b64 v[218:221], v250 offset0:152 offset1:154
	s_nop 0
	v_cvt_pk_bf16_f32 v230, v106, v107
	v_cvt_pk_bf16_f32 v231, v108, v109
	v_cvt_pk_bf16_f32 v232, v110, v111
	v_cvt_pk_bf16_f32 v233, v112, v113
	s_waitcnt lgkmcnt(2)
	s_nop 1
	v_mfma_f32_32x32x16_bf16 v[130:145], v[222:225], v[230:233], v[130:145]
	v_mfma_f32_32x32x16_bf16 v[234:249], v[226:229], v[230:233], v[234:249]
	ds_read2_b64 v[222:225], v251 offset0:124 offset1:126
	ds_read2_b64 v[226:229], v250 offset0:156 offset1:158
	s_nop 0
	v_cvt_pk_bf16_f32 v230, v114, v115
	v_cvt_pk_bf16_f32 v231, v116, v117
	v_cvt_pk_bf16_f32 v232, v118, v119
	v_cvt_pk_bf16_f32 v233, v120, v121
	s_waitcnt lgkmcnt(2)
	s_nop 1
	v_mfma_f32_32x32x16_bf16 v[130:145], v[194:197], v[230:233], v[130:145]
	v_mfma_f32_32x32x16_bf16 v[234:249], v[218:221], v[230:233], v[234:249]
	s_nop 0
	v_cvt_pk_bf16_f32 v230, v122, v123
	v_cvt_pk_bf16_f32 v231, v124, v125
	v_cvt_pk_bf16_f32 v232, v126, v127
	v_cvt_pk_bf16_f32 v233, v128, v129
	s_waitcnt lgkmcnt(0)
	s_nop 1
	v_mfma_f32_32x32x16_bf16 v[130:145], v[222:225], v[230:233], v[130:145]
	v_mfma_f32_32x32x16_bf16 v[234:249], v[226:229], v[230:233], v[234:249]
	v_fmamk_f32 v193, v192, 0x42800000, v153
	v_exp_f32_e32 v193, v193
	v_or_b32_e32 v194, 0x40000, v172
	v_mov_b32_e32 v195, v173
	v_lshl_add_u64 v[194:195], v[170:171], 0, v[194:195]
	s_nop 6
	v_mul_f32_e32 v130, v193, v130
	v_mov_b32_e32 v251, 0x7fff
	v_bfe_u32 v250, v130, 16, 1
	v_add3_u32 v130, v130, v250, v251
	global_store_short_d16_hi v[194:195], v130, off
	v_fmamk_f32 v130, v192, 0x42820000, v153
	v_exp_f32_e32 v130, v130
	s_nop 0
	v_mul_f32_e32 v130, v130, v131
	v_bfe_u32 v250, v130, 16, 1
	v_add3_u32 v193, v130, v250, v251
	v_or_b32_e32 v130, 0x41000, v172
	v_mov_b32_e32 v131, v173
	v_lshl_add_u64 v[130:131], v[170:171], 0, v[130:131]
	global_store_short_d16_hi v[130:131], v193, off
	v_fmamk_f32 v130, v192, 0x42840000, v153
	v_exp_f32_e32 v130, v130
	v_mov_b32_e32 v131, v173
	v_mul_f32_e32 v130, v130, v132
	v_bfe_u32 v250, v130, 16, 1
	v_add3_u32 v132, v130, v250, v251
	v_or_b32_e32 v130, 0x42000, v172
	v_lshl_add_u64 v[130:131], v[170:171], 0, v[130:131]
	global_store_short_d16_hi v[130:131], v132, off
	v_fmamk_f32 v130, v192, 0x42860000, v153
	v_exp_f32_e32 v130, v130
	v_mov_b32_e32 v131, v173
	v_mul_f32_e32 v130, v130, v133
	v_bfe_u32 v250, v130, 16, 1
	v_add3_u32 v132, v130, v250, v251
	v_or_b32_e32 v130, 0x43000, v172
	v_lshl_add_u64 v[130:131], v[170:171], 0, v[130:131]
	global_store_short_d16_hi v[130:131], v132, off
	v_fmamk_f32 v130, v192, 0x42900000, v153
	v_exp_f32_e32 v130, v130
	v_mov_b32_e32 v131, v173
	v_mul_f32_e32 v130, v130, v134
	v_bfe_u32 v250, v130, 16, 1
	v_add3_u32 v132, v130, v250, v251
	v_or_b32_e32 v130, 0x48000, v172
	v_lshl_add_u64 v[130:131], v[170:171], 0, v[130:131]
	global_store_short_d16_hi v[130:131], v132, off
	v_fmamk_f32 v130, v192, 0x42920000, v153
	v_exp_f32_e32 v130, v130
	v_mov_b32_e32 v131, v173
	v_mul_f32_e32 v130, v130, v135
	v_bfe_u32 v250, v130, 16, 1
	v_add3_u32 v132, v130, v250, v251
	v_or_b32_e32 v130, 0x49000, v172
	v_lshl_add_u64 v[130:131], v[170:171], 0, v[130:131]
	global_store_short_d16_hi v[130:131], v132, off
	v_fmamk_f32 v130, v192, 0x42940000, v153
	v_exp_f32_e32 v130, v130
	v_mov_b32_e32 v131, v173
	v_mul_f32_e32 v130, v130, v136
	v_bfe_u32 v250, v130, 16, 1
	v_add3_u32 v132, v130, v250, v251
	v_or_b32_e32 v130, 0x4a000, v172
	v_lshl_add_u64 v[130:131], v[170:171], 0, v[130:131]
	global_store_short_d16_hi v[130:131], v132, off
	v_fmamk_f32 v130, v192, 0x42960000, v153
	v_exp_f32_e32 v130, v130
	v_mov_b32_e32 v131, v173
	v_mul_f32_e32 v130, v130, v137
	v_bfe_u32 v250, v130, 16, 1
	v_add3_u32 v132, v130, v250, v251
	v_or_b32_e32 v130, 0x4b000, v172
	v_lshl_add_u64 v[130:131], v[170:171], 0, v[130:131]
	global_store_short_d16_hi v[130:131], v132, off
	v_fmamk_f32 v130, v192, 0x42a00000, v153
	v_exp_f32_e32 v130, v130
	v_mov_b32_e32 v131, v173
	v_mul_f32_e32 v130, v130, v138
	v_bfe_u32 v250, v130, 16, 1
	v_add3_u32 v132, v130, v250, v251
	v_or_b32_e32 v130, 0x50000, v172
	v_lshl_add_u64 v[130:131], v[170:171], 0, v[130:131]
	global_store_short_d16_hi v[130:131], v132, off
	v_fmamk_f32 v130, v192, 0x42a20000, v153
	v_exp_f32_e32 v130, v130
	v_mov_b32_e32 v131, v173
	v_mul_f32_e32 v130, v130, v139
	v_bfe_u32 v250, v130, 16, 1
	v_add3_u32 v132, v130, v250, v251
	v_or_b32_e32 v130, 0x51000, v172
	v_lshl_add_u64 v[130:131], v[170:171], 0, v[130:131]
	global_store_short_d16_hi v[130:131], v132, off
	v_fmamk_f32 v130, v192, 0x42a40000, v153
	v_exp_f32_e32 v130, v130
	v_mov_b32_e32 v131, v173
	v_mul_f32_e32 v130, v130, v140
	v_bfe_u32 v250, v130, 16, 1
	v_add3_u32 v132, v130, v250, v251
	v_or_b32_e32 v130, 0x52000, v172
	v_lshl_add_u64 v[130:131], v[170:171], 0, v[130:131]
	global_store_short_d16_hi v[130:131], v132, off
	v_fmamk_f32 v130, v192, 0x42a60000, v153
	v_exp_f32_e32 v130, v130
	v_mov_b32_e32 v131, v173
	v_mul_f32_e32 v130, v130, v141
	v_bfe_u32 v250, v130, 16, 1
	v_add3_u32 v132, v130, v250, v251
	v_or_b32_e32 v130, 0x53000, v172
	v_lshl_add_u64 v[130:131], v[170:171], 0, v[130:131]
	global_store_short_d16_hi v[130:131], v132, off
	v_fmamk_f32 v130, v192, 0x42b00000, v153
	v_exp_f32_e32 v130, v130
	v_mov_b32_e32 v131, v173
	v_mul_f32_e32 v130, v130, v142
	v_bfe_u32 v250, v130, 16, 1
	v_add3_u32 v132, v130, v250, v251
	v_or_b32_e32 v130, 0x58000, v172
	v_lshl_add_u64 v[130:131], v[170:171], 0, v[130:131]
	global_store_short_d16_hi v[130:131], v132, off
	v_fmamk_f32 v130, v192, 0x42b20000, v153
	v_exp_f32_e32 v130, v130
	v_mov_b32_e32 v131, v173
	v_mul_f32_e32 v130, v130, v143
	v_bfe_u32 v250, v130, 16, 1
	v_add3_u32 v132, v130, v250, v251
	v_or_b32_e32 v130, 0x59000, v172
	v_lshl_add_u64 v[130:131], v[170:171], 0, v[130:131]
	global_store_short_d16_hi v[130:131], v132, off
	v_fmamk_f32 v130, v192, 0x42b40000, v153
	v_exp_f32_e32 v130, v130
	v_mov_b32_e32 v131, v173
	v_mul_f32_e32 v130, v130, v144
	v_bfe_u32 v250, v130, 16, 1
	v_add3_u32 v132, v130, v250, v251
	v_or_b32_e32 v130, 0x5a000, v172
	v_lshl_add_u64 v[130:131], v[170:171], 0, v[130:131]
	global_store_short_d16_hi v[130:131], v132, off
	v_fmamk_f32 v130, v192, 0x42b60000, v153
	v_exp_f32_e32 v130, v130
	v_mov_b32_e32 v131, v173
	v_mul_f32_e32 v130, v130, v145
	v_bfe_u32 v250, v130, 16, 1
	v_add3_u32 v132, v130, v250, v251
	v_or_b32_e32 v130, 0x5b000, v172
	v_lshl_add_u64 v[130:131], v[170:171], 0, v[130:131]
	global_store_short_d16_hi v[130:131], v132, off
	v_mov_b32_e32 v130, v234
	v_mov_b32_e32 v131, v235
	v_mov_b32_e32 v132, v236
	v_mov_b32_e32 v133, v237
	v_mov_b32_e32 v134, v238
	v_mov_b32_e32 v135, v239
	v_mov_b32_e32 v136, v240
	v_mov_b32_e32 v137, v241
	v_mov_b32_e32 v138, v242
	v_mov_b32_e32 v139, v243
	v_mov_b32_e32 v140, v244
	v_mov_b32_e32 v141, v245
	v_mov_b32_e32 v142, v246
	v_mov_b32_e32 v143, v247
	v_mov_b32_e32 v144, v248
	v_mov_b32_e32 v145, v249
	v_fmamk_f32 v193, v192, 0x42c00000, v153
	v_exp_f32_e32 v193, v193
	v_or_b32_e32 v194, 0x60000, v172
	v_mov_b32_e32 v195, v173
	v_lshl_add_u64 v[194:195], v[170:171], 0, v[194:195]
	s_nop 6
	v_mul_f32_e32 v130, v193, v130
	v_mov_b32_e32 v251, 0x7fff
	v_bfe_u32 v250, v130, 16, 1
	v_add3_u32 v130, v130, v250, v251
	global_store_short_d16_hi v[194:195], v130, off
	v_fmamk_f32 v130, v192, 0x42c20000, v153
	v_exp_f32_e32 v130, v130
	s_nop 0
	v_mul_f32_e32 v130, v130, v131
	v_bfe_u32 v250, v130, 16, 1
	v_add3_u32 v193, v130, v250, v251
	v_or_b32_e32 v130, 0x61000, v172
	v_mov_b32_e32 v131, v173
	v_lshl_add_u64 v[130:131], v[170:171], 0, v[130:131]
	global_store_short_d16_hi v[130:131], v193, off
	v_fmamk_f32 v130, v192, 0x42c40000, v153
	v_exp_f32_e32 v130, v130
	v_mov_b32_e32 v131, v173
	v_mul_f32_e32 v130, v130, v132
	v_bfe_u32 v250, v130, 16, 1
	v_add3_u32 v132, v130, v250, v251
	v_or_b32_e32 v130, 0x62000, v172
	v_lshl_add_u64 v[130:131], v[170:171], 0, v[130:131]
	global_store_short_d16_hi v[130:131], v132, off
	v_fmamk_f32 v130, v192, 0x42c60000, v153
	v_exp_f32_e32 v130, v130
	v_mov_b32_e32 v131, v173
	v_mul_f32_e32 v130, v130, v133
	v_bfe_u32 v250, v130, 16, 1
	v_add3_u32 v132, v130, v250, v251
	v_or_b32_e32 v130, 0x63000, v172
	v_lshl_add_u64 v[130:131], v[170:171], 0, v[130:131]
	global_store_short_d16_hi v[130:131], v132, off
	v_fmamk_f32 v130, v192, 0x42d00000, v153
	v_exp_f32_e32 v130, v130
	v_mov_b32_e32 v131, v173
	v_mul_f32_e32 v130, v130, v134
	v_bfe_u32 v250, v130, 16, 1
	v_add3_u32 v132, v130, v250, v251
	v_or_b32_e32 v130, 0x68000, v172
	v_lshl_add_u64 v[130:131], v[170:171], 0, v[130:131]
	global_store_short_d16_hi v[130:131], v132, off
	v_fmamk_f32 v130, v192, 0x42d20000, v153
	v_exp_f32_e32 v130, v130
	v_mov_b32_e32 v131, v173
	v_mul_f32_e32 v130, v130, v135
	v_bfe_u32 v250, v130, 16, 1
	v_add3_u32 v132, v130, v250, v251
	v_or_b32_e32 v130, 0x69000, v172
	v_lshl_add_u64 v[130:131], v[170:171], 0, v[130:131]
	global_store_short_d16_hi v[130:131], v132, off
	v_fmamk_f32 v130, v192, 0x42d40000, v153
	v_exp_f32_e32 v130, v130
	v_mov_b32_e32 v131, v173
	v_mul_f32_e32 v130, v130, v136
	v_bfe_u32 v250, v130, 16, 1
	v_add3_u32 v132, v130, v250, v251
	v_or_b32_e32 v130, 0x6a000, v172
	v_lshl_add_u64 v[130:131], v[170:171], 0, v[130:131]
	global_store_short_d16_hi v[130:131], v132, off
	v_fmamk_f32 v130, v192, 0x42d60000, v153
	v_exp_f32_e32 v130, v130
	v_mov_b32_e32 v131, v173
	v_mul_f32_e32 v130, v130, v137
	v_bfe_u32 v250, v130, 16, 1
	v_add3_u32 v132, v130, v250, v251
	v_or_b32_e32 v130, 0x6b000, v172
	v_lshl_add_u64 v[130:131], v[170:171], 0, v[130:131]
	global_store_short_d16_hi v[130:131], v132, off
	v_fmamk_f32 v130, v192, 0x42e00000, v153
	v_exp_f32_e32 v130, v130
	v_mov_b32_e32 v131, v173
	v_mul_f32_e32 v130, v130, v138
	v_bfe_u32 v250, v130, 16, 1
	v_add3_u32 v132, v130, v250, v251
	v_or_b32_e32 v130, 0x70000, v172
	v_lshl_add_u64 v[130:131], v[170:171], 0, v[130:131]
	global_store_short_d16_hi v[130:131], v132, off
	v_fmamk_f32 v130, v192, 0x42e20000, v153
	v_exp_f32_e32 v130, v130
	v_mov_b32_e32 v131, v173
	v_mul_f32_e32 v130, v130, v139
	v_bfe_u32 v250, v130, 16, 1
	v_add3_u32 v132, v130, v250, v251
	v_or_b32_e32 v130, 0x71000, v172
	v_lshl_add_u64 v[130:131], v[170:171], 0, v[130:131]
	global_store_short_d16_hi v[130:131], v132, off
	v_fmamk_f32 v130, v192, 0x42e40000, v153
	v_exp_f32_e32 v130, v130
	v_mov_b32_e32 v131, v173
	v_mul_f32_e32 v130, v130, v140
	v_bfe_u32 v250, v130, 16, 1
	v_add3_u32 v132, v130, v250, v251
	v_or_b32_e32 v130, 0x72000, v172
	v_lshl_add_u64 v[130:131], v[170:171], 0, v[130:131]
	global_store_short_d16_hi v[130:131], v132, off
	v_fmamk_f32 v130, v192, 0x42e60000, v153
	v_exp_f32_e32 v130, v130
	v_mov_b32_e32 v131, v173
	v_mul_f32_e32 v130, v130, v141
	v_bfe_u32 v250, v130, 16, 1
	v_add3_u32 v132, v130, v250, v251
	v_or_b32_e32 v130, 0x73000, v172
	v_lshl_add_u64 v[130:131], v[170:171], 0, v[130:131]
	global_store_short_d16_hi v[130:131], v132, off
	v_fmamk_f32 v130, v192, 0x42f00000, v153
	v_exp_f32_e32 v130, v130
	v_mov_b32_e32 v131, v173
	v_mul_f32_e32 v130, v130, v142
	v_bfe_u32 v250, v130, 16, 1
	v_add3_u32 v132, v130, v250, v251
	v_or_b32_e32 v130, 0x78000, v172
	v_lshl_add_u64 v[130:131], v[170:171], 0, v[130:131]
	global_store_short_d16_hi v[130:131], v132, off
	v_fmamk_f32 v130, v192, 0x42f20000, v153
	v_exp_f32_e32 v130, v130
	v_mov_b32_e32 v131, v173
	v_mul_f32_e32 v130, v130, v143
	v_bfe_u32 v250, v130, 16, 1
	v_add3_u32 v132, v130, v250, v251
	v_or_b32_e32 v130, 0x79000, v172
	v_lshl_add_u64 v[130:131], v[170:171], 0, v[130:131]
	global_store_short_d16_hi v[130:131], v132, off
	v_fmamk_f32 v130, v192, 0x42f40000, v153
	v_exp_f32_e32 v130, v130
	v_mov_b32_e32 v131, v173
	v_fmac_f32_e32 v153, 0x42f60000, v192
	v_mul_f32_e32 v130, v130, v144
	v_bfe_u32 v250, v130, 16, 1
	v_add3_u32 v132, v130, v250, v251
	v_or_b32_e32 v130, 0x7a000, v172
	v_lshl_add_u64 v[130:131], v[170:171], 0, v[130:131]
	global_store_short_d16_hi v[130:131], v132, off
	v_exp_f32_e32 v130, v153
	v_or_b32_e32 v172, 0x7b000, v172
	v_mul_f32_e32 v130, v130, v145
	v_bfe_u32 v250, v130, 16, 1
	v_add3_u32 v132, v130, v250, v251
	v_lshl_add_u64 v[130:131], v[170:171], 0, v[172:173]
	global_store_short_d16_hi v[130:131], v132, off
	v_mov_b32_e32 v153, v189
	s_waitcnt vmcnt(63) expcnt(7) lgkmcnt(15)
	s_barrier
	v_lshl_add_u64 v[132:133], s[64:65], 0, v[164:165]
	v_lshlrev_b64 v[130:131], 1, v[168:169]
	v_lshlrev_b64 v[226:227], 14, v[166:167]
	v_lshl_add_u64 v[226:227], s[64:65], 0, v[226:227]
	v_lshl_add_u64 v[226:227], v[226:227], 0, v[130:131]
	v_mov_b32_e32 v228, v152
	v_mov_b32_e32 v229, v1
	v_lshl_add_u64 v[226:227], v[226:227], 0, v[228:229]
	s_mov_b64 s[6:7], 0xf640000
	v_lshl_add_u64 v[226:227], v[226:227], 0, s[6:7]
	global_load_dwordx4 v[234:237], v[226:227], off
	global_load_dwordx4 v[238:241], v[226:227], off offset:32
	global_load_dwordx4 v[242:245], v[226:227], off offset:64
	global_load_dwordx4 v[246:249], v[226:227], off offset:96
	v_lshl_add_u64 v[132:133], v[132:133], 0, v[130:131]
	v_lshlrev_b32_e32 v134, 4, v153
	v_and_b32_e32 v144, 0xf0, v134
	v_mov_b32_e32 v145, v1
	v_lshlrev_b32_e32 v134, 10, v153
	v_lshl_add_u64 v[132:133], v[132:133], 0, v[144:145]
	v_and_b32_e32 v134, 0x3c000, v134
	v_mov_b32_e32 v135, v1
	v_lshl_add_u64 v[172:173], v[132:133], 0, v[134:135]
	s_mov_b32 s6, 0xe640000
	v_add_co_u32_e64 v132, s[6:7], s6, v172
	v_bfe_u32 v145, v153, 4, 4
	s_nop 0
	v_addc_co_u32_e64 v133, s[6:7], 0, v173, s[6:7]
	s_mov_b32 s6, 0xe680000
	s_nop 0
	v_add_co_u32_e64 v136, s[6:7], s6, v172
	global_load_dwordx4 v[132:135], v[132:133], off
	s_nop 0
	v_addc_co_u32_e64 v137, s[6:7], 0, v173, s[6:7]
	s_mov_b32 s6, 0xe6c0000
	s_nop 0
	v_add_co_u32_e64 v140, s[6:7], s6, v172
	global_load_dwordx4 v[136:139], v[136:137], off
	s_nop 0
	v_addc_co_u32_e64 v141, s[6:7], 0, v173, s[6:7]
	s_mov_b32 s6, 0xe700000
	s_nop 0
	v_add_co_u32_e64 v168, s[6:7], s6, v172
	global_load_dwordx4 v[140:143], v[140:141], off
	s_nop 0
	v_addc_co_u32_e64 v169, s[6:7], 0, v173, s[6:7]
	s_mov_b32 s6, 0xe740000
	s_nop 0
	v_add_co_u32_e64 v192, s[6:7], s6, v172
	global_load_dwordx4 v[168:171], v[168:169], off
	s_nop 0
	v_addc_co_u32_e64 v193, s[6:7], 0, v173, s[6:7]
	s_mov_b32 s6, 0xe780000
	s_nop 0
	v_add_co_u32_e64 v196, s[6:7], s6, v172
	global_load_dwordx4 v[192:195], v[192:193], off
	s_nop 0
	v_addc_co_u32_e64 v197, s[6:7], 0, v173, s[6:7]
	s_mov_b32 s6, 0xe7c0000
	s_nop 0
	v_add_co_u32_e64 v208, s[6:7], s6, v172
	global_load_dwordx4 v[196:199], v[196:197], off
	s_nop 0
	v_addc_co_u32_e64 v209, s[6:7], 0, v173, s[6:7]
	s_mov_b32 s6, 0xe800000
	global_load_dwordx4 v[218:221], v[208:209], off
	v_add_co_u32_e64 v208, s[6:7], s6, v172
	v_mul_u32_u24_e32 v145, 0x108, v145
	s_nop 0
	v_addc_co_u32_e64 v209, s[6:7], 0, v173, s[6:7]
	global_load_dwordx4 v[222:225], v[208:209], off
	v_add3_u32 v153, v149, v144, v145
	s_waitcnt vmcnt(7)
	ds_write2_b64 v153, v[132:133], v[134:135] offset1:1
	v_add_u32_e32 v132, 0x1080, v153
	s_waitcnt vmcnt(6)
	ds_write2_b64 v132, v[136:137], v[138:139] offset1:1
	v_add_u32_e32 v132, 0x2100, v153
	s_waitcnt vmcnt(5)
	ds_write2_b64 v132, v[140:141], v[142:143] offset1:1
	v_add_u32_e32 v132, 0x3180, v153
	s_waitcnt vmcnt(4)
	ds_write2_b64 v132, v[168:169], v[170:171] offset1:1
	v_add_u32_e32 v132, 0x4200, v153
	s_waitcnt vmcnt(3)
	ds_write2_b64 v132, v[192:193], v[194:195] offset1:1
	v_add_u32_e32 v132, 0x5280, v153
	s_waitcnt vmcnt(2)
	ds_write2_b64 v132, v[196:197], v[198:199] offset1:1
	v_add_u32_e32 v132, 0x6300, v153
	s_waitcnt vmcnt(1)
	ds_write2_b64 v132, v[218:219], v[220:221] offset1:1
	v_add_u32_e32 v132, 0x7380, v153
	s_waitcnt vmcnt(0)
	ds_write2_b64 v132, v[222:223], v[224:225] offset1:1
	s_mov_b32 s6, 0xe840000
	v_add_co_u32_e64 v132, s[6:7], s6, v172
	s_nop 1
	v_addc_co_u32_e64 v133, s[6:7], 0, v173, s[6:7]
	s_mov_b32 s6, 0xe880000
	s_nop 0
	v_add_co_u32_e64 v136, s[6:7], s6, v172
	global_load_dwordx4 v[132:135], v[132:133], off
	s_nop 0
	v_addc_co_u32_e64 v137, s[6:7], 0, v173, s[6:7]
	s_mov_b32 s6, 0xe8c0000
	s_nop 0
	v_add_co_u32_e64 v140, s[6:7], s6, v172
	global_load_dwordx4 v[136:139], v[136:137], off
	s_nop 0
	v_addc_co_u32_e64 v141, s[6:7], 0, v173, s[6:7]
	s_mov_b32 s6, 0xe900000
	s_nop 0
	v_add_co_u32_e64 v144, s[6:7], s6, v172
	global_load_dwordx4 v[140:143], v[140:141], off
	s_nop 0
	v_addc_co_u32_e64 v145, s[6:7], 0, v173, s[6:7]
	s_mov_b32 s6, 0xe940000
	global_load_dwordx4 v[168:171], v[144:145], off
	v_add_co_u32_e64 v144, s[6:7], s6, v172
	s_nop 1
	v_addc_co_u32_e64 v145, s[6:7], 0, v173, s[6:7]
	s_mov_b32 s6, 0xe980000
	global_load_dwordx4 v[192:195], v[144:145], off
	v_add_co_u32_e64 v144, s[6:7], s6, v172
	s_nop 1
	v_addc_co_u32_e64 v145, s[6:7], 0, v173, s[6:7]
	s_mov_b32 s6, 0xe9c0000
	global_load_dwordx4 v[196:199], v[144:145], off
	v_add_co_u32_e64 v144, s[6:7], s6, v172
	s_nop 1
	v_addc_co_u32_e64 v145, s[6:7], 0, v173, s[6:7]
	s_mov_b32 s6, 0xea00000
	global_load_dwordx4 v[218:221], v[144:145], off
	v_add_co_u32_e64 v144, s[6:7], s6, v172
	s_nop 1
	v_addc_co_u32_e64 v145, s[6:7], 0, v173, s[6:7]
	global_load_dwordx4 v[222:225], v[144:145], off
	v_add_u32_e32 v144, 0x8400, v153
	s_waitcnt vmcnt(7)
	ds_write2_b64 v144, v[132:133], v[134:135] offset1:1
	v_add_u32_e32 v132, 0x9480, v153
	s_waitcnt vmcnt(6)
	ds_write2_b64 v132, v[136:137], v[138:139] offset1:1
	v_add_u32_e32 v132, 0xa500, v153
	s_waitcnt vmcnt(5)
	ds_write2_b64 v132, v[140:141], v[142:143] offset1:1
	v_add_u32_e32 v132, 0xb580, v153
	s_waitcnt vmcnt(4)
	ds_write2_b64 v132, v[168:169], v[170:171] offset1:1
	v_add_u32_e32 v132, 0xc600, v153
	s_waitcnt vmcnt(3)
	ds_write2_b64 v132, v[192:193], v[194:195] offset1:1
	v_add_u32_e32 v132, 0xd680, v153
	s_waitcnt vmcnt(2)
	ds_write2_b64 v132, v[196:197], v[198:199] offset1:1
	v_add_u32_e32 v132, 0xe700, v153
	s_waitcnt vmcnt(1)
	ds_write2_b64 v132, v[218:219], v[220:221] offset1:1
	v_add_u32_e32 v132, 0xf780, v153
	s_waitcnt vmcnt(0)
	ds_write2_b64 v132, v[222:223], v[224:225] offset1:1
	s_waitcnt lgkmcnt(0)
	s_barrier
	v_lshlrev_b64 v[132:133], 14, v[166:167]
	v_lshl_add_u64 v[132:133], s[64:65], 0, v[132:133]
	v_lshl_add_u64 v[130:131], v[132:133], 0, v[130:131]
	v_mov_b32_e32 v153, v1
	v_lshl_add_u64 v[134:135], v[130:131], 0, v[152:153]
	s_mov_b32 s6, 0xf640000
	v_add_co_u32_e64 v130, s[6:7], s6, v134
	v_mul_f32 v2, v2, v159
	v_mul_f32 v3, v3, v159
	v_mul_f32 v4, v4, v159
	v_mul_f32 v5, v5, v159
	s_nop 1
	v_addc_co_u32_e64 v131, s[6:7], 0, v135, s[6:7]
	v_mul_f32 v6, v6, v159
	v_mul_f32 v7, v7, v159
	v_mul_f32 v8, v8, v159
	v_mul_f32 v9, v9, v159
	v_mul_f32 v10, v10, v159
	v_mul_f32 v11, v11, v159
	v_mul_f32 v12, v12, v159
	v_mul_f32 v13, v13, v159
	v_mul_f32 v14, v14, v159
	v_mul_f32 v15, v15, v159
	v_mul_f32 v16, v16, v159
	v_mul_f32 v17, v17, v159
	v_mul_f32 v18, v18, v159
	v_mul_f32 v19, v19, v159
	v_mul_f32 v20, v20, v159
	v_mul_f32 v21, v21, v159
	v_mul_f32 v22, v22, v159
	v_mul_f32 v23, v23, v159
	v_mul_f32 v24, v24, v159
	v_mul_f32 v25, v25, v159
	v_mul_f32 v26, v26, v159
	v_mul_f32 v27, v27, v159
	v_mul_f32 v28, v28, v159
	v_mul_f32 v29, v29, v159
	v_mul_f32 v30, v30, v159
	v_mul_f32 v31, v31, v159
	v_mul_f32 v32, v32, v159
	v_mul_f32 v33, v33, v159
	v_mul_f32 v34, v34, v159
	v_mul_f32 v35, v35, v159
	v_mul_f32 v36, v36, v159
	v_mul_f32 v37, v37, v159
	v_mul_f32 v38, v38, v159
	v_mul_f32 v39, v39, v159
	v_mul_f32 v40, v40, v159
	v_mul_f32 v41, v41, v159
	v_mul_f32 v42, v42, v159
	v_mul_f32 v43, v43, v159
	v_mul_f32 v44, v44, v159
	v_mul_f32 v45, v45, v159
	v_mul_f32 v46, v46, v159
	v_mul_f32 v47, v47, v159
	v_mul_f32 v48, v48, v159
	v_mul_f32 v49, v49, v159
	v_mul_f32 v50, v50, v159
	v_mul_f32 v51, v51, v159
	v_mul_f32 v52, v52, v159
	v_mul_f32 v53, v53, v159
	v_mul_f32 v54, v54, v159
	v_mul_f32 v55, v55, v159
	v_mul_f32 v56, v56, v159
	v_mul_f32 v57, v57, v159
	v_mul_f32 v58, v58, v159
	v_mul_f32 v59, v59, v159
	v_mul_f32 v60, v60, v159
	v_mul_f32 v61, v61, v159
	v_mul_f32 v62, v62, v159
	v_mul_f32 v63, v63, v159
	v_mul_f32 v64, v64, v159
	v_mul_f32 v65, v65, v159
	v_mul_f32 v66, v66, v159
	v_mul_f32 v67, v67, v159
	v_mul_f32 v68, v68, v159
	v_mul_f32 v69, v69, v159
	v_mul_f32 v70, v70, v159
	v_mul_f32 v71, v71, v159
	v_mul_f32 v72, v72, v159
	v_mul_f32 v73, v73, v159
	v_mul_f32 v74, v74, v159
	v_mul_f32 v75, v75, v159
	v_mul_f32 v76, v76, v159
	v_mul_f32 v77, v77, v159
	v_mul_f32 v78, v78, v159
	v_mul_f32 v79, v79, v159
	v_mul_f32 v80, v80, v159
	v_mul_f32 v81, v81, v159
	v_mul_f32 v82, v82, v159
	v_mul_f32 v83, v83, v159
	v_mul_f32 v84, v84, v159
	v_mul_f32 v85, v85, v159
	v_mul_f32 v86, v86, v159
	v_mul_f32 v87, v87, v159
	v_mul_f32 v88, v88, v159
	v_mul_f32 v89, v89, v159
	v_mul_f32 v90, v90, v159
	v_mul_f32 v91, v91, v159
	v_mul_f32 v92, v92, v159
	v_mul_f32 v93, v93, v159
	v_mul_f32 v94, v94, v159
	v_mul_f32 v95, v95, v159
	v_mul_f32 v96, v96, v159
	v_mul_f32 v97, v97, v159
	v_mul_f32 v98, v98, v159
	v_mul_f32 v99, v99, v159
	v_mul_f32 v100, v100, v159
	v_mul_f32 v101, v101, v159
	v_mul_f32 v102, v102, v159
	v_mul_f32 v103, v103, v159
	v_mul_f32 v104, v104, v159
	v_mul_f32 v105, v105, v159
	v_mul_f32 v106, v106, v159
	v_mul_f32 v107, v107, v159
	v_mul_f32 v108, v108, v159
	v_mul_f32 v109, v109, v159
	v_mul_f32 v110, v110, v159
	v_mul_f32 v111, v111, v159
	v_mul_f32 v112, v112, v159
	v_mul_f32 v113, v113, v159
	v_mul_f32 v114, v114, v159
	v_mul_f32 v115, v115, v159
	v_mul_f32 v116, v116, v159
	v_mul_f32 v117, v117, v159
	v_mul_f32 v118, v118, v159
	v_mul_f32 v119, v119, v159
	v_mul_f32 v120, v120, v159
	v_mul_f32 v121, v121, v159
	v_mul_f32 v122, v122, v159
	v_mul_f32 v123, v123, v159
	v_mul_f32 v124, v124, v159
	v_mul_f32 v125, v125, v159
	v_mul_f32 v126, v126, v159
	v_mul_f32 v127, v127, v159
	v_mul_f32 v128, v128, v159
	v_mul_f32 v129, v129, v159
	s_mov_b64 s[6:7], 0xf640000
	v_lshl_add_u64 v[142:143], v[134:135], 0, s[6:7]
	v_mov_b32_e32 v130, v234
	v_mov_b32_e32 v131, v235
	v_mov_b32_e32 v132, v236
	v_mov_b32_e32 v133, v237
	v_mov_b32_e32 v134, v238
	v_mov_b32_e32 v135, v239
	v_mov_b32_e32 v136, v240
	v_mov_b32_e32 v137, v241
	v_mov_b32_e32 v138, v242
	v_mov_b32_e32 v139, v243
	v_mov_b32_e32 v140, v244
	v_mov_b32_e32 v141, v245
	v_mov_b32_e32 v166, v246
	v_mov_b32_e32 v167, v247
	v_mov_b32_e32 v168, v248
	v_mov_b32_e32 v169, v249
	global_load_dwordx4 v[234:237], v[142:143], off offset:128
	global_load_dwordx4 v[238:241], v[142:143], off offset:160
	global_load_dwordx4 v[242:245], v[142:143], off offset:192
	global_load_dwordx4 v[246:249], v[142:143], off offset:224
	v_fma_f32 v144, 0, v191, v190
	v_add_f32_e32 v145, v190, v191
	v_exp_f32_e32 v144, v144
	v_exp_f32_e32 v145, v145
	v_fmamk_f32 v153, v191, 0x42480000, v190
	s_waitcnt vmcnt(4)
	v_lshlrev_b32_e32 v170, 16, v130
	v_and_b32_e32 v171, 0xffff0000, v130
	v_fma_f32 v130, 2.0, v191, v190
	v_pk_mul_f32 v[144:145], v[144:145], v[170:171]
	v_exp_f32_e32 v170, v130
	v_fmamk_f32 v130, v191, 0x40400000, v190
	v_exp_f32_e32 v171, v130
	v_cvt_pk_bf16_f32 v130, v144, v145
	v_lshlrev_b32_e32 v144, 16, v131
	v_and_b32_e32 v145, 0xffff0000, v131
	v_fma_f32 v131, 4.0, v191, v190
	v_pk_mul_f32 v[144:145], v[170:171], v[144:145]
	v_exp_f32_e32 v170, v131
	v_fmamk_f32 v131, v191, 0x40a00000, v190
	v_exp_f32_e32 v171, v131
	v_cvt_pk_bf16_f32 v131, v144, v145
	v_lshlrev_b32_e32 v144, 16, v132
	v_and_b32_e32 v145, 0xffff0000, v132
	v_fmamk_f32 v132, v191, 0x40c00000, v190
	v_pk_mul_f32 v[144:145], v[170:171], v[144:145]
	v_exp_f32_e32 v170, v132
	v_fmamk_f32 v132, v191, 0x40e00000, v190
	v_exp_f32_e32 v171, v132
	v_cvt_pk_bf16_f32 v132, v144, v145
	v_lshlrev_b32_e32 v144, 16, v133
	v_and_b32_e32 v145, 0xffff0000, v133
	v_fmamk_f32 v133, v191, 0x41800000, v190
	v_pk_mul_f32 v[144:145], v[170:171], v[144:145]
	v_exp_f32_e32 v170, v133
	v_fmamk_f32 v133, v191, 0x41880000, v190
	v_exp_f32_e32 v171, v133
	v_cvt_pk_bf16_f32 v133, v144, v145
	s_waitcnt vmcnt(4)
	v_lshlrev_b32_e32 v144, 16, v134
	v_and_b32_e32 v145, 0xffff0000, v134
	v_fmamk_f32 v134, v191, 0x41900000, v190
	v_pk_mul_f32 v[144:145], v[170:171], v[144:145]
	v_exp_f32_e32 v170, v134
	v_fmamk_f32 v134, v191, 0x41980000, v190
	v_exp_f32_e32 v171, v134
	v_cvt_pk_bf16_f32 v134, v144, v145
	v_lshlrev_b32_e32 v144, 16, v135
	v_and_b32_e32 v145, 0xffff0000, v135
	v_fmamk_f32 v135, v191, 0x41a00000, v190
	v_pk_mul_f32 v[144:145], v[170:171], v[144:145]
	v_exp_f32_e32 v170, v135
	v_fmamk_f32 v135, v191, 0x41a80000, v190
	v_exp_f32_e32 v171, v135
	v_cvt_pk_bf16_f32 v135, v144, v145
	v_lshlrev_b32_e32 v144, 16, v136
	v_and_b32_e32 v145, 0xffff0000, v136
	v_fmamk_f32 v136, v191, 0x41b00000, v190
	v_pk_mul_f32 v[144:145], v[170:171], v[144:145]
	v_exp_f32_e32 v170, v136
	v_fmamk_f32 v136, v191, 0x41b80000, v190
	v_exp_f32_e32 v171, v136
	v_cvt_pk_bf16_f32 v136, v144, v145
	v_lshlrev_b32_e32 v144, 16, v137
	v_and_b32_e32 v145, 0xffff0000, v137
	v_fmamk_f32 v137, v191, 0x42000000, v190
	v_pk_mul_f32 v[144:145], v[170:171], v[144:145]
	v_exp_f32_e32 v170, v137
	v_fmamk_f32 v137, v191, 0x42040000, v190
	v_exp_f32_e32 v171, v137
	v_cvt_pk_bf16_f32 v137, v144, v145
	s_waitcnt vmcnt(4)
	v_lshlrev_b32_e32 v144, 16, v138
	v_and_b32_e32 v145, 0xffff0000, v138
	v_fmamk_f32 v138, v191, 0x42080000, v190
	v_pk_mul_f32 v[144:145], v[170:171], v[144:145]
	v_exp_f32_e32 v170, v138
	v_fmamk_f32 v138, v191, 0x420c0000, v190
	v_exp_f32_e32 v171, v138
	v_cvt_pk_bf16_f32 v138, v144, v145
	v_lshlrev_b32_e32 v144, 16, v139
	v_and_b32_e32 v145, 0xffff0000, v139
	v_fmamk_f32 v139, v191, 0x42100000, v190
	v_pk_mul_f32 v[144:145], v[170:171], v[144:145]
	v_exp_f32_e32 v170, v139
	v_fmamk_f32 v139, v191, 0x42140000, v190
	v_exp_f32_e32 v171, v139
	v_cvt_pk_bf16_f32 v139, v144, v145
	v_lshlrev_b32_e32 v144, 16, v140
	v_and_b32_e32 v145, 0xffff0000, v140
	v_fmamk_f32 v140, v191, 0x42180000, v190
	v_pk_mul_f32 v[144:145], v[170:171], v[144:145]
	v_exp_f32_e32 v170, v140
	v_fmamk_f32 v140, v191, 0x421c0000, v190
	v_exp_f32_e32 v171, v140
	v_cvt_pk_bf16_f32 v140, v144, v145
	v_lshlrev_b32_e32 v144, 16, v141
	v_and_b32_e32 v145, 0xffff0000, v141
	v_fmamk_f32 v141, v191, 0x42400000, v190
	v_pk_mul_f32 v[144:145], v[170:171], v[144:145]
	v_exp_f32_e32 v170, v141
	v_fmamk_f32 v141, v191, 0x42440000, v190
	v_exp_f32_e32 v171, v141
	v_cvt_pk_bf16_f32 v141, v144, v145
	s_waitcnt vmcnt(4)
	v_lshlrev_b32_e32 v144, 16, v166
	v_and_b32_e32 v145, 0xffff0000, v166
	v_pk_mul_f32 v[144:145], v[170:171], v[144:145]
	v_exp_f32_e32 v170, v153
	v_fmamk_f32 v153, v191, 0x424c0000, v190
	v_exp_f32_e32 v171, v153
	v_cvt_pk_bf16_f32 v166, v144, v145
	v_lshlrev_b32_e32 v144, 16, v167
	v_and_b32_e32 v145, 0xffff0000, v167
	v_fmamk_f32 v153, v191, 0x42500000, v190
	v_pk_mul_f32 v[144:145], v[170:171], v[144:145]
	v_exp_f32_e32 v170, v153
	v_fmamk_f32 v153, v191, 0x42540000, v190
	v_exp_f32_e32 v171, v153
	v_cvt_pk_bf16_f32 v167, v144, v145
	v_lshlrev_b32_e32 v144, 16, v168
	v_and_b32_e32 v145, 0xffff0000, v168
	v_fmamk_f32 v153, v191, 0x42580000, v190
	v_pk_mul_f32 v[144:145], v[170:171], v[144:145]
	v_exp_f32_e32 v170, v153
	v_fmamk_f32 v153, v191, 0x425c0000, v190
	v_exp_f32_e32 v171, v153
	v_cvt_pk_bf16_f32 v168, v144, v145
	v_lshlrev_b32_e32 v144, 16, v169
	v_and_b32_e32 v145, 0xffff0000, v169
	v_pk_mul_f32 v[144:145], v[170:171], v[144:145]
	s_nop 0
	v_cvt_pk_bf16_f32 v169, v144, v145
	ds_read2_b64 v[170:173], v179 offset1:1
	ds_read2_b64 v[192:195], v179 offset0:4 offset1:5
	ds_read2_b64 v[196:199], v179 offset0:8 offset1:9
	ds_read2_b64 v[218:221], v179 offset0:12 offset1:13
	s_waitcnt lgkmcnt(3)
	v_mfma_f32_32x32x16_bf16 v[2:17], v[170:173], v[130:133], v[2:17]
	v_add_u32_e32 v144, 0x2100, v179
	ds_read2_b64 v[170:173], v144 offset1:1
	s_waitcnt lgkmcnt(3)
	v_mfma_f32_32x32x16_bf16 v[2:17], v[192:195], v[134:137], v[2:17]
	v_add_u32_e32 v144, 0x2120, v179
	ds_read2_b64 v[192:195], v144 offset1:1
	s_waitcnt lgkmcnt(3)
	v_mfma_f32_32x32x16_bf16 v[2:17], v[196:199], v[138:141], v[2:17]
	v_add_u32_e32 v144, 0x2140, v179
	ds_read2_b64 v[196:199], v144 offset1:1
	s_waitcnt lgkmcnt(3)
	v_mfma_f32_32x32x16_bf16 v[2:17], v[218:221], v[166:169], v[2:17]
	v_add_u32_e32 v144, 0x2160, v179
	ds_read2_b64 v[218:221], v144 offset1:1
	s_waitcnt lgkmcnt(3)
	v_mfma_f32_32x32x16_bf16 v[18:33], v[170:173], v[130:133], v[18:33]
	v_add_u32_e32 v144, 0x4200, v179
	ds_read2_b64 v[170:173], v144 offset1:1
	s_waitcnt lgkmcnt(3)
	v_mfma_f32_32x32x16_bf16 v[18:33], v[192:195], v[134:137], v[18:33]
	v_add_u32_e32 v144, 0x4220, v179
	ds_read2_b64 v[192:195], v144 offset1:1
	s_waitcnt lgkmcnt(3)
	v_mfma_f32_32x32x16_bf16 v[18:33], v[196:199], v[138:141], v[18:33]
	v_add_u32_e32 v144, 0x4240, v179
	ds_read2_b64 v[196:199], v144 offset1:1
	s_waitcnt lgkmcnt(3)
	v_mfma_f32_32x32x16_bf16 v[18:33], v[218:221], v[166:169], v[18:33]
	v_add_u32_e32 v144, 0x4260, v179
	ds_read2_b64 v[218:221], v144 offset1:1
	s_waitcnt lgkmcnt(3)
	v_mfma_f32_32x32x16_bf16 v[34:49], v[170:173], v[130:133], v[34:49]
	v_add_u32_e32 v144, 0x6300, v179
	ds_read2_b64 v[170:173], v144 offset1:1
	s_waitcnt lgkmcnt(3)
	v_mfma_f32_32x32x16_bf16 v[34:49], v[192:195], v[134:137], v[34:49]
	v_add_u32_e32 v144, 0x6320, v179
	ds_read2_b64 v[192:195], v144 offset1:1
	s_waitcnt lgkmcnt(3)
	v_mfma_f32_32x32x16_bf16 v[34:49], v[196:199], v[138:141], v[34:49]
	v_add_u32_e32 v144, 0x6340, v179
	ds_read2_b64 v[196:199], v144 offset1:1
	s_waitcnt lgkmcnt(3)
	v_mfma_f32_32x32x16_bf16 v[34:49], v[218:221], v[166:169], v[34:49]
	v_add_u32_e32 v144, 0x6360, v179
	ds_read2_b64 v[218:221], v144 offset1:1
	s_waitcnt lgkmcnt(3)
	v_mfma_f32_32x32x16_bf16 v[50:65], v[170:173], v[130:133], v[50:65]
	v_add_u32_e32 v144, 0x8400, v179
	ds_read2_b64 v[170:173], v144 offset1:1
	s_waitcnt lgkmcnt(3)
	v_mfma_f32_32x32x16_bf16 v[50:65], v[192:195], v[134:137], v[50:65]
	v_add_u32_e32 v144, 0x8420, v179
	ds_read2_b64 v[192:195], v144 offset1:1
	s_waitcnt lgkmcnt(3)
	v_mfma_f32_32x32x16_bf16 v[50:65], v[196:199], v[138:141], v[50:65]
	v_add_u32_e32 v144, 0x8440, v179
	ds_read2_b64 v[196:199], v144 offset1:1
	s_waitcnt lgkmcnt(3)
	v_mfma_f32_32x32x16_bf16 v[50:65], v[218:221], v[166:169], v[50:65]
	v_add_u32_e32 v144, 0x8460, v179
	ds_read2_b64 v[218:221], v144 offset1:1
	s_waitcnt lgkmcnt(3)
	v_mfma_f32_32x32x16_bf16 v[66:81], v[170:173], v[130:133], v[66:81]
	v_add_u32_e32 v144, 0xa500, v179
	ds_read2_b64 v[170:173], v144 offset1:1
	s_waitcnt lgkmcnt(3)
	v_mfma_f32_32x32x16_bf16 v[66:81], v[192:195], v[134:137], v[66:81]
	v_add_u32_e32 v144, 0xa520, v179
	ds_read2_b64 v[192:195], v144 offset1:1
	s_waitcnt lgkmcnt(3)
	v_mfma_f32_32x32x16_bf16 v[66:81], v[196:199], v[138:141], v[66:81]
	v_add_u32_e32 v144, 0xa540, v179
	ds_read2_b64 v[196:199], v144 offset1:1
	s_waitcnt lgkmcnt(3)
	v_mfma_f32_32x32x16_bf16 v[66:81], v[218:221], v[166:169], v[66:81]
	v_add_u32_e32 v144, 0xa560, v179
	ds_read2_b64 v[218:221], v144 offset1:1
	s_waitcnt lgkmcnt(3)
	v_mfma_f32_32x32x16_bf16 v[82:97], v[170:173], v[130:133], v[82:97]
	v_add_u32_e32 v144, 0xc600, v179
	ds_read2_b64 v[170:173], v144 offset1:1
	s_waitcnt lgkmcnt(3)
	v_mfma_f32_32x32x16_bf16 v[82:97], v[192:195], v[134:137], v[82:97]
	v_add_u32_e32 v144, 0xc620, v179
	ds_read2_b64 v[192:195], v144 offset1:1
	s_waitcnt lgkmcnt(3)
	v_mfma_f32_32x32x16_bf16 v[82:97], v[196:199], v[138:141], v[82:97]
	v_add_u32_e32 v144, 0xc640, v179
	ds_read2_b64 v[196:199], v144 offset1:1
	s_waitcnt lgkmcnt(3)
	v_mfma_f32_32x32x16_bf16 v[82:97], v[218:221], v[166:169], v[82:97]
	v_add_u32_e32 v144, 0xc660, v179
	ds_read2_b64 v[218:221], v144 offset1:1
	s_waitcnt lgkmcnt(3)
	v_mfma_f32_32x32x16_bf16 v[98:113], v[170:173], v[130:133], v[98:113]
	v_add_u32_e32 v144, 0xe700, v179
	ds_read2_b64 v[170:173], v144 offset1:1
	s_waitcnt lgkmcnt(3)
	v_mfma_f32_32x32x16_bf16 v[98:113], v[192:195], v[134:137], v[98:113]
	v_add_u32_e32 v144, 0xe720, v179
	ds_read2_b64 v[192:195], v144 offset1:1
	s_waitcnt lgkmcnt(3)
	v_mfma_f32_32x32x16_bf16 v[98:113], v[196:199], v[138:141], v[98:113]
	v_add_u32_e32 v144, 0xe740, v179
	ds_read2_b64 v[196:199], v144 offset1:1
	s_waitcnt lgkmcnt(3)
	v_mfma_f32_32x32x16_bf16 v[98:113], v[218:221], v[166:169], v[98:113]
	v_add_u32_e32 v144, 0xe760, v179
	ds_read2_b64 v[218:221], v144 offset1:1
	s_waitcnt lgkmcnt(3)
	v_mfma_f32_32x32x16_bf16 v[114:129], v[170:173], v[130:133], v[114:129]
	s_waitcnt lgkmcnt(2)
	v_mfma_f32_32x32x16_bf16 v[114:129], v[192:195], v[134:137], v[114:129]
	s_waitcnt lgkmcnt(1)
	v_mfma_f32_32x32x16_bf16 v[114:129], v[196:199], v[138:141], v[114:129]
	s_waitcnt lgkmcnt(0)
	v_mfma_f32_32x32x16_bf16 v[114:129], v[218:221], v[166:169], v[114:129]
	v_fmamk_f32 v134, v191, 0x42800000, v190
	v_fmamk_f32 v135, v191, 0x42820000, v190
	v_exp_f32_e32 v134, v134
	v_exp_f32_e32 v135, v135
	v_fmamk_f32 v138, v191, 0x42a00000, v190
	v_fmamk_f32 v139, v191, 0x42a20000, v190
	v_exp_f32_e32 v138, v138
	v_exp_f32_e32 v139, v139
	v_fmamk_f32 v144, v191, 0x42c00000, v190
	v_fmamk_f32 v145, v191, 0x42c20000, v190
	v_exp_f32_e32 v144, v144
	v_exp_f32_e32 v145, v145
	v_fmamk_f32 v153, v191, 0x42e00000, v190
	s_waitcnt vmcnt(0)
	v_mov_b32_e32 v130, v234
	v_mov_b32_e32 v131, v235
	v_mov_b32_e32 v132, v236
	v_mov_b32_e32 v133, v237
	v_lshlrev_b32_e32 v136, 16, v130
	v_and_b32_e32 v137, 0xffff0000, v130
	v_pk_mul_f32 v[134:135], v[134:135], v[136:137]
	v_lshlrev_b32_e32 v136, 16, v131
	v_cvt_pk_bf16_f32 v130, v134, v135
	v_fmamk_f32 v134, v191, 0x42840000, v190
	v_fmamk_f32 v135, v191, 0x42860000, v190
	v_exp_f32_e32 v134, v134
	v_exp_f32_e32 v135, v135
	v_and_b32_e32 v137, 0xffff0000, v131
	v_pk_mul_f32 v[134:135], v[134:135], v[136:137]
	s_nop 0
	v_cvt_pk_bf16_f32 v131, v134, v135
	v_fmamk_f32 v134, v191, 0x42880000, v190
	v_fmamk_f32 v135, v191, 0x428a0000, v190
	v_exp_f32_e32 v134, v134
	v_exp_f32_e32 v135, v135
	v_lshlrev_b32_e32 v136, 16, v132
	v_and_b32_e32 v137, 0xffff0000, v132
	v_pk_mul_f32 v[134:135], v[134:135], v[136:137]
	s_nop 0
	v_cvt_pk_bf16_f32 v132, v134, v135
	v_fmamk_f32 v134, v191, 0x428c0000, v190
	v_fmamk_f32 v135, v191, 0x428e0000, v190
	v_exp_f32_e32 v134, v134
	v_exp_f32_e32 v135, v135
	v_lshlrev_b32_e32 v136, 16, v133
	v_and_b32_e32 v137, 0xffff0000, v133
	v_pk_mul_f32 v[134:135], v[134:135], v[136:137]
	s_nop 0
	v_cvt_pk_bf16_f32 v133, v134, v135
	s_waitcnt vmcnt(0)
	v_mov_b32_e32 v134, v238
	v_mov_b32_e32 v135, v239
	v_mov_b32_e32 v136, v240
	v_mov_b32_e32 v137, v241
	v_lshlrev_b32_e32 v140, 16, v134
	v_and_b32_e32 v141, 0xffff0000, v134
	v_pk_mul_f32 v[138:139], v[138:139], v[140:141]
	v_lshlrev_b32_e32 v140, 16, v135
	v_cvt_pk_bf16_f32 v134, v138, v139
	v_fmamk_f32 v138, v191, 0x42a40000, v190
	v_fmamk_f32 v139, v191, 0x42a60000, v190
	v_exp_f32_e32 v138, v138
	v_exp_f32_e32 v139, v139
	v_and_b32_e32 v141, 0xffff0000, v135
	v_pk_mul_f32 v[138:139], v[138:139], v[140:141]
	s_nop 0
	v_cvt_pk_bf16_f32 v135, v138, v139
	v_fmamk_f32 v138, v191, 0x42a80000, v190
	v_fmamk_f32 v139, v191, 0x42aa0000, v190
	v_exp_f32_e32 v138, v138
	v_exp_f32_e32 v139, v139
	v_lshlrev_b32_e32 v140, 16, v136
	v_and_b32_e32 v141, 0xffff0000, v136
	v_pk_mul_f32 v[138:139], v[138:139], v[140:141]
	s_nop 0
	v_cvt_pk_bf16_f32 v136, v138, v139
	v_fmamk_f32 v138, v191, 0x42ac0000, v190
	v_fmamk_f32 v139, v191, 0x42ae0000, v190
	v_exp_f32_e32 v138, v138
	v_exp_f32_e32 v139, v139
	v_lshlrev_b32_e32 v140, 16, v137
	v_and_b32_e32 v141, 0xffff0000, v137
	v_pk_mul_f32 v[138:139], v[138:139], v[140:141]
	s_nop 0
	v_cvt_pk_bf16_f32 v137, v138, v139
	s_waitcnt vmcnt(0)
	v_mov_b32_e32 v138, v242
	v_mov_b32_e32 v139, v243
	v_mov_b32_e32 v140, v244
	v_mov_b32_e32 v141, v245
	v_lshlrev_b32_e32 v166, 16, v138
	v_and_b32_e32 v167, 0xffff0000, v138
	v_pk_mul_f32 v[144:145], v[144:145], v[166:167]
	v_lshlrev_b32_e32 v166, 16, v139
	v_cvt_pk_bf16_f32 v138, v144, v145
	v_fmamk_f32 v144, v191, 0x42c40000, v190
	v_fmamk_f32 v145, v191, 0x42c60000, v190
	v_exp_f32_e32 v144, v144
	v_exp_f32_e32 v145, v145
	v_and_b32_e32 v167, 0xffff0000, v139
	v_pk_mul_f32 v[144:145], v[144:145], v[166:167]
	s_nop 0
	v_cvt_pk_bf16_f32 v139, v144, v145
	v_fmamk_f32 v144, v191, 0x42c80000, v190
	v_fmamk_f32 v145, v191, 0x42ca0000, v190
	v_exp_f32_e32 v144, v144
	v_exp_f32_e32 v145, v145
	v_lshlrev_b32_e32 v166, 16, v140
	v_and_b32_e32 v167, 0xffff0000, v140
	v_pk_mul_f32 v[144:145], v[144:145], v[166:167]
	s_nop 0
	v_cvt_pk_bf16_f32 v140, v144, v145
	v_fmamk_f32 v144, v191, 0x42cc0000, v190
	v_fmamk_f32 v145, v191, 0x42ce0000, v190
	v_exp_f32_e32 v144, v144
	v_exp_f32_e32 v145, v145
	v_lshlrev_b32_e32 v166, 16, v141
	v_and_b32_e32 v167, 0xffff0000, v141
	v_pk_mul_f32 v[144:145], v[144:145], v[166:167]
	s_nop 0
	v_cvt_pk_bf16_f32 v141, v144, v145
	v_exp_f32_e32 v166, v153
	v_fmamk_f32 v153, v191, 0x42e20000, v190
	v_exp_f32_e32 v167, v153
	v_fmamk_f32 v153, v191, 0x42e40000, v190
	s_waitcnt vmcnt(0)
	v_mov_b32_e32 v142, v246
	v_mov_b32_e32 v143, v247
	v_mov_b32_e32 v144, v248
	v_mov_b32_e32 v145, v249
	v_lshlrev_b32_e32 v168, 16, v142
	v_and_b32_e32 v169, 0xffff0000, v142
	v_pk_mul_f32 v[166:167], v[166:167], v[168:169]
	v_lshlrev_b32_e32 v168, 16, v143
	v_cvt_pk_bf16_f32 v142, v166, v167
	v_exp_f32_e32 v166, v153
	v_fmamk_f32 v153, v191, 0x42e60000, v190
	v_exp_f32_e32 v167, v153
	v_and_b32_e32 v169, 0xffff0000, v143
	v_fmamk_f32 v153, v191, 0x42e80000, v190
	v_pk_mul_f32 v[166:167], v[166:167], v[168:169]
	s_nop 0
	v_cvt_pk_bf16_f32 v143, v166, v167
	v_exp_f32_e32 v166, v153
	v_fmamk_f32 v153, v191, 0x42ea0000, v190
	v_exp_f32_e32 v167, v153
	v_lshlrev_b32_e32 v168, 16, v144
	v_and_b32_e32 v169, 0xffff0000, v144
	v_fmamk_f32 v153, v191, 0x42ec0000, v190
	v_pk_mul_f32 v[166:167], v[166:167], v[168:169]
	v_fmac_f32_e32 v190, 0x42ee0000, v191
	v_cvt_pk_bf16_f32 v144, v166, v167
	v_exp_f32_e32 v166, v153
	v_exp_f32_e32 v167, v190
	v_lshlrev_b32_e32 v168, 16, v145
	v_and_b32_e32 v169, 0xffff0000, v145
	v_pk_mul_f32 v[166:167], v[166:167], v[168:169]
	s_nop 0
	v_cvt_pk_bf16_f32 v145, v166, v167
	ds_read2_b64 v[166:169], v179 offset0:16 offset1:17
	ds_read2_b64 v[170:173], v179 offset0:20 offset1:21
	ds_read2_b64 v[190:193], v179 offset0:24 offset1:25
	ds_read2_b64 v[194:197], v179 offset0:28 offset1:29
	s_waitcnt lgkmcnt(3)
	v_mfma_f32_32x32x16_bf16 v[2:17], v[166:169], v[130:133], v[2:17]
	v_add_u32_e32 v153, 0x2180, v179
	ds_read2_b64 v[166:169], v153 offset1:1
	s_waitcnt lgkmcnt(3)
	v_mfma_f32_32x32x16_bf16 v[2:17], v[170:173], v[134:137], v[2:17]
	v_add_u32_e32 v153, 0x21a0, v179
	ds_read2_b64 v[170:173], v153 offset1:1
	s_waitcnt lgkmcnt(3)
	v_mfma_f32_32x32x16_bf16 v[2:17], v[190:193], v[138:141], v[2:17]
	v_add_u32_e32 v153, 0x21c0, v179
	ds_read2_b64 v[190:193], v153 offset1:1
	s_waitcnt lgkmcnt(3)
	v_mfma_f32_32x32x16_bf16 v[2:17], v[194:197], v[142:145], v[2:17]
	v_add_u32_e32 v153, 0x21e0, v179
	ds_read2_b64 v[194:197], v153 offset1:1
	s_waitcnt lgkmcnt(3)
	v_mfma_f32_32x32x16_bf16 v[18:33], v[166:169], v[130:133], v[18:33]
	v_add_u32_e32 v153, 0x4280, v179
	ds_read2_b64 v[166:169], v153 offset1:1
	s_waitcnt lgkmcnt(3)
	v_mfma_f32_32x32x16_bf16 v[18:33], v[170:173], v[134:137], v[18:33]
	v_add_u32_e32 v153, 0x42a0, v179
	ds_read2_b64 v[170:173], v153 offset1:1
	s_waitcnt lgkmcnt(3)
	v_mfma_f32_32x32x16_bf16 v[18:33], v[190:193], v[138:141], v[18:33]
	v_add_u32_e32 v153, 0x42c0, v179
	ds_read2_b64 v[190:193], v153 offset1:1
	s_waitcnt lgkmcnt(3)
	v_mfma_f32_32x32x16_bf16 v[18:33], v[194:197], v[142:145], v[18:33]
	v_add_u32_e32 v153, 0x42e0, v179
	ds_read2_b64 v[194:197], v153 offset1:1
	s_waitcnt lgkmcnt(3)
	v_mfma_f32_32x32x16_bf16 v[34:49], v[166:169], v[130:133], v[34:49]
	v_add_u32_e32 v153, 0x6380, v179
	ds_read2_b64 v[166:169], v153 offset1:1
	s_waitcnt lgkmcnt(3)
	v_mfma_f32_32x32x16_bf16 v[34:49], v[170:173], v[134:137], v[34:49]
	v_add_u32_e32 v153, 0x63a0, v179
	ds_read2_b64 v[170:173], v153 offset1:1
	s_waitcnt lgkmcnt(3)
	v_mfma_f32_32x32x16_bf16 v[34:49], v[190:193], v[138:141], v[34:49]
	v_add_u32_e32 v153, 0x63c0, v179
	ds_read2_b64 v[190:193], v153 offset1:1
	s_waitcnt lgkmcnt(3)
	v_mfma_f32_32x32x16_bf16 v[34:49], v[194:197], v[142:145], v[34:49]
	v_add_u32_e32 v153, 0x63e0, v179
	ds_read2_b64 v[194:197], v153 offset1:1
	s_waitcnt lgkmcnt(3)
	v_mfma_f32_32x32x16_bf16 v[50:65], v[166:169], v[130:133], v[50:65]
	v_add_u32_e32 v153, 0x8480, v179
	ds_read2_b64 v[166:169], v153 offset1:1
	s_waitcnt lgkmcnt(3)
	v_mfma_f32_32x32x16_bf16 v[50:65], v[170:173], v[134:137], v[50:65]
	v_add_u32_e32 v153, 0x84a0, v179
	ds_read2_b64 v[170:173], v153 offset1:1
	s_waitcnt lgkmcnt(3)
	v_mfma_f32_32x32x16_bf16 v[50:65], v[190:193], v[138:141], v[50:65]
	v_add_u32_e32 v153, 0x84c0, v179
	ds_read2_b64 v[190:193], v153 offset1:1
	s_waitcnt lgkmcnt(3)
	v_mfma_f32_32x32x16_bf16 v[50:65], v[194:197], v[142:145], v[50:65]
	v_add_u32_e32 v153, 0x84e0, v179
	ds_read2_b64 v[194:197], v153 offset1:1
	s_waitcnt lgkmcnt(3)
	v_mfma_f32_32x32x16_bf16 v[66:81], v[166:169], v[130:133], v[66:81]
	v_add_u32_e32 v153, 0xa580, v179
	ds_read2_b64 v[166:169], v153 offset1:1
	s_waitcnt lgkmcnt(3)
	v_mfma_f32_32x32x16_bf16 v[66:81], v[170:173], v[134:137], v[66:81]
	v_add_u32_e32 v153, 0xa5a0, v179
	ds_read2_b64 v[170:173], v153 offset1:1
	s_waitcnt lgkmcnt(3)
	v_mfma_f32_32x32x16_bf16 v[66:81], v[190:193], v[138:141], v[66:81]
	v_add_u32_e32 v153, 0xa5c0, v179
	ds_read2_b64 v[190:193], v153 offset1:1
	s_waitcnt lgkmcnt(3)
	v_mfma_f32_32x32x16_bf16 v[66:81], v[194:197], v[142:145], v[66:81]
	v_add_u32_e32 v153, 0xa5e0, v179
	ds_read2_b64 v[194:197], v153 offset1:1
	s_waitcnt lgkmcnt(3)
	v_mfma_f32_32x32x16_bf16 v[82:97], v[166:169], v[130:133], v[82:97]
	v_add_u32_e32 v153, 0xc680, v179
	ds_read2_b64 v[166:169], v153 offset1:1
	s_waitcnt lgkmcnt(3)
	v_mfma_f32_32x32x16_bf16 v[82:97], v[170:173], v[134:137], v[82:97]
	v_add_u32_e32 v153, 0xc6a0, v179
	ds_read2_b64 v[170:173], v153 offset1:1
	s_waitcnt lgkmcnt(3)
	v_mfma_f32_32x32x16_bf16 v[82:97], v[190:193], v[138:141], v[82:97]
	v_add_u32_e32 v153, 0xc6c0, v179
	ds_read2_b64 v[190:193], v153 offset1:1
	s_waitcnt lgkmcnt(3)
	v_mfma_f32_32x32x16_bf16 v[82:97], v[194:197], v[142:145], v[82:97]
	v_add_u32_e32 v153, 0xc6e0, v179
	ds_read2_b64 v[194:197], v153 offset1:1
	s_waitcnt lgkmcnt(3)
	v_mfma_f32_32x32x16_bf16 v[98:113], v[166:169], v[130:133], v[98:113]
	v_add_u32_e32 v153, 0xe780, v179
	ds_read2_b64 v[166:169], v153 offset1:1
	s_waitcnt lgkmcnt(3)
	v_mfma_f32_32x32x16_bf16 v[98:113], v[170:173], v[134:137], v[98:113]
	v_add_u32_e32 v153, 0xe7a0, v179
	ds_read2_b64 v[170:173], v153 offset1:1
	s_waitcnt lgkmcnt(3)
	v_mfma_f32_32x32x16_bf16 v[98:113], v[190:193], v[138:141], v[98:113]
	v_add_u32_e32 v153, 0xe7c0, v179
	ds_read2_b64 v[190:193], v153 offset1:1
	s_waitcnt lgkmcnt(3)
	v_mfma_f32_32x32x16_bf16 v[98:113], v[194:197], v[142:145], v[98:113]
	v_add_u32_e32 v153, 0xe7e0, v179
	ds_read2_b64 v[194:197], v153 offset1:1
	s_waitcnt lgkmcnt(3)
	v_mfma_f32_32x32x16_bf16 v[114:129], v[166:169], v[130:133], v[114:129]
	s_waitcnt lgkmcnt(2)
	v_mfma_f32_32x32x16_bf16 v[114:129], v[170:173], v[134:137], v[114:129]
	s_waitcnt lgkmcnt(1)
	v_mfma_f32_32x32x16_bf16 v[114:129], v[190:193], v[138:141], v[114:129]
	s_waitcnt lgkmcnt(0)
	v_mfma_f32_32x32x16_bf16 v[114:129], v[194:197], v[142:145], v[114:129]
	s_add_i32 s66, s66, 1
	s_add_i32 s67, s67, -1
	s_cmp_eq_u32 s67, -1
	s_cbranch_scc0 .LBB0_327
	s_and_b64 vcc, exec, s[4:5]
	s_mov_b64 s[4:5], -1
	s_cbranch_vccnz .LBB0_330
	s_mov_b64 s[4:5], 0
